# PEER expert phase restructured: slice-major fp6 tables, 8 U + 8 V slice passes per wave so gathers stay L2-resident; software-pipelined row loads
# speedup vs baseline: 1.1081x; 1.0736x over previous
.LBB0_130:
	v_mov_b32_e32 v16, v186
	v_readlane_b32 s4, v242, 0
	v_ashrrev_i32_e32 v17, 6, v16
	s_nop 0
	v_add_u32_e32 v17, s4, v17
	s_nop 0
	v_readfirstlane_b32 s10, v17
	s_cmpk_gt_i32 s10, 0x7fff
	s_cbranch_scc1 .LBB0_99
	s_load_dword s4, s[80:81], 0x10
	v_and_b32_e32 v17, 63, v16
	v_lshlrev_b32_e32 v16, 2, v17
	v_lshrrev_b32_e32 v36, 3, v17
	v_mul_u32_u24_e32 v36, 3, v36
	v_lshlrev_b32_e32 v36, 20, v36
	v_and_b32_e32 v37, 7, v17
	v_lshl_add_u32 v32, v37, 4, v36
	v_lshl_add_u32 v34, v37, 3, v36
	s_waitcnt lgkmcnt(0)
	s_lshr_b32 s4, s4, 16
	s_cmp_lg_u32 s4, 0
	s_cselect_b64 s[4:5], -1, 0
	s_cmp_lg_u64 s[4:5], 0
	s_addc_u32 s4, s78, 0
	s_lshl_b32 s11, s4, 3
	v_cmp_eq_u32_e64 s[4:5], 0, v17
	v_xor_b32_e32 v17, 1, v179
	v_cmp_lt_i32_e32 vcc, v17, v151
	v_mov_b32_e32 v33, v177
	v_mov_b32_e32 v35, v177
	v_cndmask_b32_e32 v17, v179, v17, vcc
	v_lshlrev_b32_e32 v36, 2, v17
	v_xor_b32_e32 v17, 2, v179
	v_cmp_lt_i32_e32 vcc, v17, v151
	v_lshlrev_b32_e32 v176, 2, v16
	s_nop 0
	v_cndmask_b32_e32 v17, v179, v17, vcc
	v_lshlrev_b32_e32 v37, 2, v17
	v_xor_b32_e32 v17, 4, v179
	v_cmp_lt_i32_e32 vcc, v17, v151
	s_nop 1
	v_cndmask_b32_e32 v17, v179, v17, vcc
	v_lshlrev_b32_e32 v38, 2, v17
	v_xor_b32_e32 v17, 8, v179
	v_cmp_lt_i32_e32 vcc, v17, v151
	s_nop 1
	v_cndmask_b32_e32 v17, v179, v17, vcc
	v_lshlrev_b32_e32 v39, 2, v17
	v_xor_b32_e32 v17, 16, v179
	v_cmp_lt_i32_e32 vcc, v17, v151
	s_nop 1
	v_cndmask_b32_e32 v17, v179, v17, vcc
	v_lshlrev_b32_e32 v40, 2, v17
	s_branch .LBB0_133

.LBB0_133:
	s_and_b32 s12, s10, 0x3fff
	s_lshl_b32 s13, s12, 13
	s_cmpk_gt_i32 s10, 0x3fff
	s_cselect_b64 s[6:7], -1, 0
	s_and_b64 s[8:9], s[6:7], exec
	s_cselect_b32 s14, s66, s64
	s_cselect_b32 s15, s67, s65
	s_cselect_b32 s8, s71, s69
	s_cselect_b32 s9, s70, s68
	s_add_u32 s14, s14, s13
	s_addc_u32 s15, s15, 0
	v_lshl_add_u64 v[42:43], s[14:15], 0, v[176:177]
	global_load_dwordx4 v[16:19], v176, s[14:15]
	global_load_dwordx4 v[20:23], v176, s[14:15] offset:1024
	global_load_dwordx4 v[24:27], v176, s[14:15] offset:2048
	global_load_dwordx4 v[28:31], v176, s[14:15] offset:3072
	v_add_co_u32_e32 v54, vcc, s92, v42
	s_mul_i32 s13, s12, 0xc0
	s_nop 0
	v_addc_co_u32_e32 v55, vcc, 0, v43, vcc
	global_load_dwordx4 v[42:45], v[54:55], off
	global_load_dwordx4 v[46:49], v[54:55], off offset:1024
	global_load_dwordx4 v[50:53], v[54:55], off offset:2048
	s_nop 0
	global_load_dwordx4 v[54:57], v[54:55], off offset:3072
	s_waitcnt vmcnt(7)
	v_max_f32_e64 v41, |v19|, |v19|
	v_max_f32_e64 v58, |v18|, |v18|
	s_waitcnt vmcnt(6)
	v_max_f32_e64 v59, |v23|, |v23|
	v_max_f32_e64 v60, |v22|, |v22|
	s_waitcnt vmcnt(5)
	v_max_f32_e64 v61, |v27|, |v27|
	v_max_f32_e64 v62, |v26|, |v26|
	s_waitcnt vmcnt(4)
	v_max_f32_e64 v63, |v31|, |v31|
	v_max_f32_e64 v64, |v30|, |v30|
	v_max_f32_e32 v41, v58, v41
	v_max_f32_e32 v58, v60, v59
	v_max_f32_e32 v59, v62, v61
	v_max_f32_e32 v60, v64, v63
	v_max3_f32 v41, |v16|, |v17|, v41
	v_max3_f32 v58, |v20|, |v21|, v58
	s_waitcnt vmcnt(3)
	v_max_f32_e64 v61, |v45|, |v45|
	v_max_f32_e64 v62, |v44|, |v44|
	s_waitcnt vmcnt(2)
	v_max_f32_e64 v63, |v49|, |v49|
	v_max_f32_e64 v64, |v48|, |v48|
	v_max3_f32 v59, |v24|, |v25|, v59
	v_max3_f32 v60, |v28|, |v29|, v60
	s_waitcnt vmcnt(1)
	v_max_f32_e64 v65, |v53|, |v53|
	v_max_f32_e64 v66, |v52|, |v52|
	s_waitcnt vmcnt(0)
	v_max_f32_e64 v67, |v57|, |v57|
	v_max_f32_e64 v68, |v56|, |v56|
	v_max3_f32 v41, v41, 0, v58
	v_max_f32_e32 v58, v62, v61
	v_max_f32_e32 v61, v64, v63
	v_max_f32_e32 v62, v66, v65
	v_max_f32_e32 v63, v68, v67
	v_max3_f32 v41, v41, v59, v60
	v_max3_f32 v58, |v42|, |v43|, v58
	v_max3_f32 v59, |v46|, |v47|, v61
	v_max3_f32 v60, |v50|, |v51|, v62
	v_max3_f32 v61, |v54|, |v55|, v63
	v_max3_f32 v41, v41, v58, v59
	v_max3_f32 v41, v41, v60, v61
	ds_bpermute_b32 v58, v36, v41
	v_mov_b32_e32 v59, v18
	v_pk_mov_b32 v[18:19], v[18:19], v[20:21] op_sel:[1,0]
	v_mov_b32_e32 v20, v21
	v_mov_b32_e32 v21, v22
	s_waitcnt lgkmcnt(0)
	v_max_f32_e32 v58, v58, v58
	v_max_f32_e32 v41, v41, v58
	ds_bpermute_b32 v60, v37, v41
	v_mov_b32_e32 v58, v17
	v_pk_mov_b32 v[22:23], v[22:23], v[24:25] op_sel:[1,0]
	v_mov_b32_e32 v24, v25
	s_waitcnt lgkmcnt(0)
	v_max_f32_e32 v17, v60, v60
	v_max_f32_e32 v17, v41, v17
	ds_bpermute_b32 v41, v38, v17
	s_waitcnt lgkmcnt(0)
	v_max_f32_e32 v25, v41, v41
	v_max_f32_e32 v17, v17, v25
	ds_bpermute_b32 v41, v39, v17
	v_mov_b32_e32 v25, v26
	v_pk_mov_b32 v[26:27], v[26:27], v[28:29] op_sel:[1,0]
	v_mov_b32_e32 v28, v29
	v_mov_b32_e32 v29, v30
	s_waitcnt lgkmcnt(0)
	v_max_f32_e32 v30, v41, v41
	v_max_f32_e32 v17, v17, v30
	ds_bpermute_b32 v41, v40, v17
	v_pk_mov_b32 v[30:31], v[30:31], v[42:43] op_sel:[1,0]
	v_mov_b32_e32 v42, v43
	v_mov_b32_e32 v43, v44
	v_pk_mov_b32 v[44:45], v[44:45], v[46:47] op_sel:[1,0]
	s_waitcnt lgkmcnt(0)
	v_max_f32_e32 v41, v41, v41
	v_max_f32_e32 v17, v17, v41
	ds_bpermute_b32 v41, v150, v17
	v_mov_b32_e32 v46, v47
	v_mov_b32_e32 v47, v48
	v_pk_mov_b32 v[48:49], v[48:49], v[50:51] op_sel:[1,0]
	v_mov_b32_e32 v50, v51
	s_waitcnt lgkmcnt(0)
	v_max_f32_e32 v41, v41, v41
	v_max_f32_e32 v41, v17, v41
	v_div_scale_f32 v17, s[14:15], v41, v41, s94
	v_rcp_f32_e32 v60, v17
	v_mov_b32_e32 v51, v52
	v_div_scale_f32 v52, vcc, s94, v41, s94
	v_fma_f32 v61, -v17, v60, 1.0
	v_fmac_f32_e32 v60, v61, v60
	v_mul_f32_e32 v61, v52, v60
	v_fma_f32 v62, -v17, v61, v52
	v_fmac_f32_e32 v61, v62, v60
	v_fma_f32 v17, -v17, v61, v52
	v_div_fmas_f32 v17, v17, v60, v61
	v_div_fixup_f32 v17, v17, v41, s94
	v_cmp_lt_f32_e32 vcc, 0, v41
	s_add_u32 s14, s9, s13
	s_addc_u32 s15, s8, 0
	v_cndmask_b32_e32 v52, 1.0, v17, vcc
	v_pk_mul_f32 v[18:19], v[18:19], v[52:53] op_sel_hi:[1,0]
	v_pk_mul_f32 v[20:21], v[20:21], v[52:53] op_sel_hi:[1,0]
	v_pk_mul_f32 v[24:25], v[24:25], v[52:53] op_sel_hi:[1,0]
	v_pk_mul_f32 v[30:31], v[30:31], v[52:53] op_sel_hi:[1,0]
	v_cvt_pk_f16_f32 v18, v18, v19
	v_cvt_pk_f16_f32 v19, v20, v21
	v_cvt_pk_f16_f32 v21, v24, v25
	v_cvt_pk_f16_f32 v24, v30, v31
	v_pk_mov_b32 v[30:31], v[52:53], v[54:55] op_sel:[1,0]
	v_pk_mul_f32 v[42:43], v[42:43], v[52:53] op_sel_hi:[1,0]
	v_pk_mul_f32 v[30:31], v[30:31], v[52:53] op_sel_hi:[1,0]
	v_cvt_pk_f16_f32 v25, v42, v43
	v_cvt_pk_f16_f32 v42, v30, v31
	v_mov_b32_e32 v30, v55
	v_mov_b32_e32 v31, v56
	v_pk_mul_f32 v[30:31], v[30:31], v[52:53] op_sel_hi:[1,0]
	v_fma_mixlo_f16 v60, v16, v52, 0
	v_pk_mul_f32 v[16:17], v[58:59], v[52:53] op_sel_hi:[1,0]
	v_pk_mul_f32 v[22:23], v[22:23], v[52:53] op_sel_hi:[1,0]
	v_pk_mul_f32 v[26:27], v[26:27], v[52:53] op_sel_hi:[1,0]
	v_pk_mul_f32 v[28:29], v[28:29], v[52:53] op_sel_hi:[1,0]
	v_pk_mul_f32 v[44:45], v[44:45], v[52:53] op_sel_hi:[1,0]
	v_pk_mul_f32 v[46:47], v[46:47], v[52:53] op_sel_hi:[1,0]
	v_pk_mul_f32 v[48:49], v[48:49], v[52:53] op_sel_hi:[1,0]
	v_pk_mul_f32 v[50:51], v[50:51], v[52:53] op_sel_hi:[1,0]
	v_cvt_pk_f16_f32 v31, v30, v31
	v_cvt_pk_f16_f32 v17, v16, v17
	v_cvt_pk_f16_f32 v20, v22, v23
	v_cvt_pk_f16_f32 v22, v26, v27
	v_cvt_pk_f16_f32 v23, v28, v29
	v_cvt_pk_f16_f32 v26, v44, v45
	v_cvt_pk_f16_f32 v27, v46, v47
	v_cvt_pk_f16_f32 v28, v48, v49
	v_cvt_pk_f16_f32 v29, v50, v51
	v_alignbit_b32 v30, v31, v42, 16
	v_lshrrev_b32_e32 v31, 16, v31
	v_pack_b32_f16 v16, v60, v17
	v_alignbit_b32 v17, v18, v17, 16
	v_alignbit_b32 v18, v19, v18, 16
	v_alignbit_b32 v19, v20, v19, 16
	v_alignbit_b32 v20, v21, v20, 16
	v_alignbit_b32 v21, v22, v21, 16
	v_alignbit_b32 v22, v23, v22, 16
	v_alignbit_b32 v23, v24, v23, 16
	v_alignbit_b32 v24, v25, v24, 16
	v_alignbit_b32 v25, v26, v25, 16
	v_alignbit_b32 v26, v27, v26, 16
	v_alignbit_b32 v27, v28, v27, 16
	v_alignbit_b32 v28, v29, v28, 16
	v_alignbit_b32 v29, v42, v29, 16
	v_fma_mixhi_f16 v31, v57, v52, 0
	v_cvt_scalef32_pk32_fp6_f16 v[42:47], v[16:31], 1.0
	v_lshl_add_u64 v[16:17], s[14:15], 0, v[32:33]
	global_store_dwordx4 v[16:17], v[42:45], off
	v_lshl_add_u64 v[16:17], s[14:15], 0, v[34:35]
	global_store_dwordx2 v[16:17], v[46:47], off offset:128
	s_and_saveexec_b64 s[8:9], s[4:5]
	s_cbranch_execz .LBB0_132
	s_and_b64 s[6:7], s[6:7], exec
	s_cselect_b32 s7, s59, s57
	s_cselect_b32 s6, s58, s56
	s_lshl_b32 s12, s12, 2
	v_mul_f32_e32 v16, 0x3e124925, v41
	v_cndmask_b32_e32 v16, 1.0, v16, vcc
	v_mov_b32_e32 v17, s12
	global_store_dword v17, v16, s[6:7]
	s_branch .LBB0_132

.LBB0_145:
	v_mov_b32_e32 v0, v186
	v_readlane_b32 s4, v242, 0
	v_ashrrev_i32_e32 v1, 6, v0
	s_nop 0
	v_add_u32_e32 v1, s4, v1
	s_nop 0
	v_readfirstlane_b32 s10, v1
	s_cmpk_gt_i32 s10, 0x7fff
	s_cbranch_scc1 .LBB0_150
	s_load_dword s4, s[80:81], 0x10
	v_and_b32_e32 v1, 63, v0
	v_and_b32_e32 v2, 64, v179
	v_lshlrev_b32_e32 v0, 2, v1
	v_add_u32_e32 v2, 64, v2
	s_waitcnt lgkmcnt(0)
	s_lshr_b32 s4, s4, 16
	s_cmp_lg_u32 s4, 0
	s_cselect_b64 s[4:5], -1, 0
	s_cmp_lg_u64 s[4:5], 0
	s_addc_u32 s4, s78, 0
	s_lshl_b32 s11, s4, 3
	v_lshrrev_b32_e32 v16, 3, v1
	v_mul_u32_u24_e32 v16, 3, v16
	v_lshlrev_b32_e32 v16, 20, v16
	v_and_b32_e32 v18, 7, v1
	v_lshl_add_u32 v3, v18, 4, v16
	v_lshl_add_u32 v18, v18, 3, v16
	v_mov_b32_e32 v16, v3
	v_cmp_eq_u32_e64 s[4:5], 0, v1
	v_xor_b32_e32 v1, 1, v179
	v_cmp_lt_i32_e32 vcc, v1, v2
	v_mov_b32_e32 v17, 0
	v_mov_b32_e32 v19, v17
	v_cndmask_b32_e32 v1, v179, v1, vcc
	v_lshlrev_b32_e32 v22, 2, v1
	v_xor_b32_e32 v1, 2, v179
	v_cmp_lt_i32_e32 vcc, v1, v2
	v_lshlrev_b32_e32 v20, 2, v0
	v_mov_b32_e32 v21, v17
	v_cndmask_b32_e32 v1, v179, v1, vcc
	v_lshlrev_b32_e32 v23, 2, v1
	v_xor_b32_e32 v1, 4, v179
	v_cmp_lt_i32_e32 vcc, v1, v2
	s_movk_i32 s12, 0x1000
	s_mov_b32 s13, 0x40e00000
	v_cndmask_b32_e32 v1, v179, v1, vcc
	v_lshlrev_b32_e32 v24, 2, v1
	v_xor_b32_e32 v1, 8, v179
	v_cmp_lt_i32_e32 vcc, v1, v2
	s_nop 1
	v_cndmask_b32_e32 v1, v179, v1, vcc
	v_lshlrev_b32_e32 v25, 2, v1
	v_xor_b32_e32 v1, 16, v179
	v_cmp_lt_i32_e32 vcc, v1, v2
	s_nop 1
	v_cndmask_b32_e32 v1, v179, v1, vcc
	v_lshlrev_b32_e32 v26, 2, v1
	v_xor_b32_e32 v1, 32, v179
	v_cmp_lt_i32_e32 vcc, v1, v2
	s_nop 1
	v_cndmask_b32_e32 v1, v179, v1, vcc
	v_lshlrev_b32_e32 v27, 2, v1
	s_branch .LBB0_148

.LBB0_148:
	s_and_b32 s14, s10, 0x3fff
	s_lshl_b32 s15, s14, 13
	s_cmpk_gt_i32 s10, 0x3fff
	s_cselect_b64 s[6:7], -1, 0
	s_and_b64 s[8:9], s[6:7], exec
	s_cselect_b32 s16, s66, s64
	s_cselect_b32 s17, s67, s65
	s_cselect_b32 s8, s71, s69
	s_cselect_b32 s9, s70, s68
	s_add_u32 s16, s16, s15
	s_addc_u32 s17, s17, 0
	v_lshl_add_u64 v[28:29], s[16:17], 0, v[20:21]
	global_load_dwordx4 v[0:3], v20, s[16:17]
	global_load_dwordx4 v[4:7], v20, s[16:17] offset:1024
	global_load_dwordx4 v[8:11], v20, s[16:17] offset:2048
	global_load_dwordx4 v[12:15], v20, s[16:17] offset:3072
	v_add_co_u32_e32 v44, vcc, s12, v28
	s_mul_i32 s15, s14, 0xc0
	s_nop 0
	v_addc_co_u32_e32 v45, vcc, 0, v29, vcc
	global_load_dwordx4 v[28:31], v[44:45], off
	global_load_dwordx4 v[32:35], v[44:45], off offset:1024
	global_load_dwordx4 v[36:39], v[44:45], off offset:2048
	global_load_dwordx4 v[40:43], v[44:45], off offset:3072
	s_waitcnt vmcnt(7)
	v_max_f32_e64 v44, |v3|, |v3|
	v_max_f32_e64 v45, |v2|, |v2|
	s_waitcnt vmcnt(6)
	v_max_f32_e64 v46, |v7|, |v7|
	v_max_f32_e64 v47, |v6|, |v6|
	s_waitcnt vmcnt(5)
	v_max_f32_e64 v48, |v11|, |v11|
	v_max_f32_e64 v49, |v10|, |v10|
	s_waitcnt vmcnt(4)
	v_max_f32_e64 v50, |v15|, |v15|
	v_max_f32_e64 v51, |v14|, |v14|
	v_max_f32_e32 v44, v45, v44
	v_max_f32_e32 v45, v47, v46
	v_max_f32_e32 v46, v49, v48
	v_max_f32_e32 v47, v51, v50
	v_max3_f32 v44, |v0|, |v1|, v44
	v_max3_f32 v45, |v4|, |v5|, v45
	s_waitcnt vmcnt(3)
	v_max_f32_e64 v48, |v31|, |v31|
	v_max_f32_e64 v49, |v30|, |v30|
	s_waitcnt vmcnt(2)
	v_max_f32_e64 v50, |v35|, |v35|
	v_max_f32_e64 v51, |v34|, |v34|
	v_max3_f32 v46, |v8|, |v9|, v46
	v_max3_f32 v47, |v12|, |v13|, v47
	s_waitcnt vmcnt(1)
	v_max_f32_e64 v52, |v39|, |v39|
	v_max_f32_e64 v53, |v38|, |v38|
	s_waitcnt vmcnt(0)
	v_max_f32_e64 v54, |v43|, |v43|
	v_max_f32_e64 v55, |v42|, |v42|
	v_max3_f32 v44, v44, 0, v45
	v_max_f32_e32 v45, v49, v48
	v_max_f32_e32 v48, v51, v50
	v_max_f32_e32 v49, v53, v52
	v_max_f32_e32 v50, v55, v54
	v_max3_f32 v44, v44, v46, v47
	v_max3_f32 v45, |v28|, |v29|, v45
	v_max3_f32 v46, |v32|, |v33|, v48
	v_max3_f32 v47, |v36|, |v37|, v49
	v_max3_f32 v48, |v40|, |v41|, v50
	v_max3_f32 v44, v44, v45, v46
	v_max3_f32 v44, v44, v47, v48
	ds_bpermute_b32 v45, v22, v44
	s_waitcnt lgkmcnt(0)
	v_max_f32_e32 v45, v45, v45
	v_max_f32_e32 v46, v44, v45
	ds_bpermute_b32 v47, v23, v46
	v_mov_b32_e32 v44, v1
	v_mov_b32_e32 v45, v2
	v_pk_mov_b32 v[2:3], v[2:3], v[4:5] op_sel:[1,0]
	v_mov_b32_e32 v4, v5
	s_waitcnt lgkmcnt(0)
	v_max_f32_e32 v1, v47, v47
	v_max_f32_e32 v1, v46, v1
	ds_bpermute_b32 v46, v24, v1
	v_mov_b32_e32 v5, v6
	v_pk_mov_b32 v[6:7], v[6:7], v[8:9] op_sel:[1,0]
	v_mov_b32_e32 v8, v9
	v_mov_b32_e32 v47, v30
	s_waitcnt lgkmcnt(0)
	v_max_f32_e32 v9, v46, v46
	v_max_f32_e32 v1, v1, v9
	ds_bpermute_b32 v46, v25, v1
	v_mov_b32_e32 v9, v10
	v_pk_mov_b32 v[10:11], v[10:11], v[12:13] op_sel:[1,0]
	v_mov_b32_e32 v12, v13
	v_mov_b32_e32 v13, v14
	s_waitcnt lgkmcnt(0)
	v_max_f32_e32 v14, v46, v46
	v_max_f32_e32 v1, v1, v14
	ds_bpermute_b32 v48, v26, v1
	v_pk_mov_b32 v[14:15], v[14:15], v[28:29] op_sel:[1,0]
	v_mov_b32_e32 v46, v29
	v_pk_mov_b32 v[30:31], v[30:31], v[32:33] op_sel:[1,0]
	v_mov_b32_e32 v32, v33
	s_waitcnt lgkmcnt(0)
	v_max_f32_e32 v28, v48, v48
	v_max_f32_e32 v1, v1, v28
	ds_bpermute_b32 v28, v27, v1
	v_mov_b32_e32 v33, v34
	v_pk_mov_b32 v[34:35], v[34:35], v[36:37] op_sel:[1,0]
	v_mov_b32_e32 v36, v37
	v_mov_b32_e32 v37, v38
	s_waitcnt lgkmcnt(0)
	v_max_f32_e32 v28, v28, v28
	v_max_f32_e32 v28, v1, v28
	v_div_scale_f32 v1, s[16:17], v28, v28, s13
	v_rcp_f32_e32 v29, v1
	v_div_scale_f32 v48, vcc, s13, v28, s13
	s_add_u32 s16, s9, s15
	v_fma_f32 v49, -v1, v29, 1.0
	v_fmac_f32_e32 v29, v49, v29
	v_mul_f32_e32 v49, v48, v29
	v_fma_f32 v50, -v1, v49, v48
	v_fmac_f32_e32 v49, v50, v29
	v_fma_f32 v1, -v1, v49, v48
	v_div_fmas_f32 v1, v1, v29, v49
	v_div_fixup_f32 v1, v1, v28, s13
	v_cmp_lt_f32_e32 vcc, 0, v28
	s_addc_u32 s17, s8, 0
	s_nop 0
	v_cndmask_b32_e32 v48, 1.0, v1, vcc
	v_pk_mul_f32 v[2:3], v[2:3], v[48:49] op_sel_hi:[1,0]
	v_pk_mul_f32 v[4:5], v[4:5], v[48:49] op_sel_hi:[1,0]
	v_pk_mul_f32 v[8:9], v[8:9], v[48:49] op_sel_hi:[1,0]
	v_pk_mul_f32 v[14:15], v[14:15], v[48:49] op_sel_hi:[1,0]
	v_fma_mixlo_f16 v29, v0, v48, 0
	v_pk_mul_f32 v[0:1], v[44:45], v[48:49] op_sel_hi:[1,0]
	v_cvt_pk_f16_f32 v2, v2, v3
	v_cvt_pk_f16_f32 v3, v4, v5
	v_cvt_pk_f16_f32 v5, v8, v9
	v_cvt_pk_f16_f32 v8, v14, v15
	v_pk_mov_b32 v[14:15], v[38:39], v[40:41] op_sel:[1,0]
	v_cvt_pk_f16_f32 v1, v0, v1
	v_pk_mul_f32 v[14:15], v[14:15], v[48:49] op_sel_hi:[1,0]
	v_pack_b32_f16 v0, v29, v1
	v_cvt_pk_f16_f32 v29, v14, v15
	v_mov_b32_e32 v14, v41
	v_mov_b32_e32 v15, v42
	v_pk_mul_f32 v[14:15], v[14:15], v[48:49] op_sel_hi:[1,0]
	v_pk_mul_f32 v[6:7], v[6:7], v[48:49] op_sel_hi:[1,0]
	v_pk_mul_f32 v[10:11], v[10:11], v[48:49] op_sel_hi:[1,0]
	v_pk_mul_f32 v[12:13], v[12:13], v[48:49] op_sel_hi:[1,0]
	v_pk_mul_f32 v[44:45], v[46:47], v[48:49] op_sel_hi:[1,0]
	v_pk_mul_f32 v[30:31], v[30:31], v[48:49] op_sel_hi:[1,0]
	v_pk_mul_f32 v[32:33], v[32:33], v[48:49] op_sel_hi:[1,0]
	v_pk_mul_f32 v[34:35], v[34:35], v[48:49] op_sel_hi:[1,0]
	v_pk_mul_f32 v[36:37], v[36:37], v[48:49] op_sel_hi:[1,0]
	v_cvt_pk_f16_f32 v15, v14, v15
	v_cvt_pk_f16_f32 v4, v6, v7
	v_cvt_pk_f16_f32 v6, v10, v11
	v_cvt_pk_f16_f32 v7, v12, v13
	v_cvt_pk_f16_f32 v9, v44, v45
	v_cvt_pk_f16_f32 v10, v30, v31
	v_cvt_pk_f16_f32 v11, v32, v33
	v_cvt_pk_f16_f32 v12, v34, v35
	v_cvt_pk_f16_f32 v13, v36, v37
	v_alignbit_b32 v14, v15, v29, 16
	v_lshrrev_b32_e32 v15, 16, v15
	v_alignbit_b32 v1, v2, v1, 16
	v_alignbit_b32 v2, v3, v2, 16
	v_alignbit_b32 v3, v4, v3, 16
	v_alignbit_b32 v4, v5, v4, 16
	v_alignbit_b32 v5, v6, v5, 16
	v_alignbit_b32 v6, v7, v6, 16
	v_alignbit_b32 v7, v8, v7, 16
	v_alignbit_b32 v8, v9, v8, 16
	v_alignbit_b32 v9, v10, v9, 16
	v_alignbit_b32 v10, v11, v10, 16
	v_alignbit_b32 v11, v12, v11, 16
	v_alignbit_b32 v12, v13, v12, 16
	v_alignbit_b32 v13, v29, v13, 16
	v_fma_mixhi_f16 v15, v43, v48, 0
	v_cvt_scalef32_pk32_fp6_f16 v[30:35], v[0:15], 1.0
	v_lshl_add_u64 v[0:1], s[16:17], 0, v[16:17]
	global_store_dwordx4 v[0:1], v[30:33], off
	v_lshl_add_u64 v[0:1], s[16:17], 0, v[18:19]
	global_store_dwordx2 v[0:1], v[34:35], off offset:128
	s_and_saveexec_b64 s[8:9], s[4:5]
	s_cbranch_execz .LBB0_147
	s_and_b64 s[6:7], s[6:7], exec
	s_cselect_b32 s7, s59, s57
	s_cselect_b32 s6, s58, s56
	s_lshl_b32 s14, s14, 2
	v_mul_f32_e32 v0, 0x3e124925, v28
	v_cndmask_b32_e32 v0, 1.0, v0, vcc
	v_mov_b32_e32 v1, s14
	global_store_dword v1, v0, s[6:7]
	s_branch .LBB0_147

.LBB0_217:
	s_or_b64 exec, exec, s[4:5]
	s_barrier
	v_readlane_b32 s2, v242, 0
	v_ashrrev_i32_e32 v0, 6, v186
	s_nop 0
	v_add_u32_e32 v0, s2, v0
	s_nop 0
	v_readfirstlane_b32 s4, v0
	s_mov_b32 s5, s76
	s_cmpk_gt_i32 s4, 0x3fff
	s_cbranch_scc1 .LBB0_226
	s_load_dwordx2 s[28:29], s[0:1], 0xb0
	s_load_dwordx2 s[26:27], s[0:1], 0xc0
	s_load_dwordx4 s[16:19], s[0:1], 0xf0
	s_load_dwordx2 s[10:11], s[0:1], 0x100
	s_load_dwordx4 s[20:23], s[0:1], 0x108
	s_load_dwordx4 s[12:15], s[0:1], 0x148
	s_load_dwordx2 s[24:25], s[0:1], 0x158
	v_and_b32_e32 v228, 63, v186
	v_and_b32_e32 v212, 7, v228
	v_lshrrev_b32_e32 v213, 3, v228
	v_lshlrev_b32_e32 v220, 4, v212
	v_lshlrev_b32_e32 v224, 3, v212
	v_sub_u32_e32 v221, 0x80, v224
	v_bfrev_b32_e32 v214, v213
	v_lshrrev_b32_e32 v214, 29, v214
	v_lshl_add_u32 v225, v214, 9, v224
	v_lshl_add_u32 v226, v214, 10, v220
	v_xor_b32_e32 v227, 32, v228
	v_lshlrev_b32_e32 v227, 2, v227
	v_mov_b32_e32 v231, 0
	v_lshrrev_b32_e32 v215, 6, v186
	s_nop 0
	v_readfirstlane_b32 s64, v215
	s_lshl_b32 s64, s64, 13
	s_add_i32 s64, s64, 16
	v_lshl_add_u32 v222, v228, 3, s64
	v_lshl_add_u32 v223, v213, 6, s64
	v_lshl_add_u32 v230, v228, 2, s64
	v_add_u32_e32 v229, 0x1000, v223
	s_mov_b32 s40, 0xaaaaaaaa
	s_mov_b32 s41, 0xaaaaaaaa
	s_mov_b32 s42, 0xcccccccc
	s_mov_b32 s43, 0xcccccccc
	s_mov_b32 s44, 0xf0f0f0f0
	s_mov_b32 s45, 0xf0f0f0f0
	s_mov_b32 s46, 0xff00ff00
	s_mov_b32 s47, 0xff00ff00
	s_mov_b32 s48, 0xffff0000
	s_mov_b32 s49, 0xffff0000
	s_mov_b32 s50, 0
	s_mov_b32 s51, -1
	s_movk_i32 s52, 0xc0
	s_mov_b32 s66, 0x378e98ab
	s_mov_b32 s67, 0xb9c68948
	s_mov_b32 s68, 0x3b7cd369
	s_mov_b32 s69, 0xbcc618b2
	s_mov_b32 s70, 0x3dda74e4
	s_mov_b32 s71, 0x3f228afd
	s_mov_b32 s72, 0x3e03c728
	s_mov_b32 s73, 0xbfb8aa3b
	s_mov_b32 s74, 0x42ce8ed0
	s_mov_b32 s75, 0xc2b17218
	s_mov_b32 s76, 0x3ba10414
	s_mov_b32 s77, 0x7fffffff
	s_mov_b32 s6, s4
	s_waitcnt lgkmcnt(0)
.Lex_chunk:
	s_movk_i32 s36, 0
	s_mul_i32 s37, s36, s5
	s_add_i32 s37, s37, s6
	s_min_u32 s37, s37, 0x3fff
	s_lshl_b32 s37, s37, 9
	s_add_u32 s82, s12, s37
	s_addc_u32 s83, s13, 0
	v_lshlrev_b32_e32 v219, 2, v228
	global_load_dword v96, v219, s[82:83]
	global_load_dword v97, v219, s[82:83] offset:256
	s_movk_i32 s36, 1
	s_mul_i32 s37, s36, s5
	s_add_i32 s37, s37, s6
	s_min_u32 s37, s37, 0x3fff
	s_lshl_b32 s37, s37, 9
	s_add_u32 s82, s12, s37
	s_addc_u32 s83, s13, 0
	v_lshlrev_b32_e32 v219, 2, v228
	global_load_dword v98, v219, s[82:83]
	global_load_dword v99, v219, s[82:83] offset:256
	s_movk_i32 s36, 2
	s_mul_i32 s37, s36, s5
	s_add_i32 s37, s37, s6
	s_min_u32 s37, s37, 0x3fff
	s_lshl_b32 s37, s37, 9
	s_add_u32 s82, s12, s37
	s_addc_u32 s83, s13, 0
	v_lshlrev_b32_e32 v219, 2, v228
	global_load_dword v100, v219, s[82:83]
	global_load_dword v101, v219, s[82:83] offset:256
	s_movk_i32 s36, 3
	s_mul_i32 s37, s36, s5
	s_add_i32 s37, s37, s6
	s_min_u32 s37, s37, 0x3fff
	s_lshl_b32 s37, s37, 9
	s_add_u32 s82, s12, s37
	s_addc_u32 s83, s13, 0
	v_lshlrev_b32_e32 v219, 2, v228
	global_load_dword v102, v219, s[82:83]
	global_load_dword v103, v219, s[82:83] offset:256
	s_movk_i32 s36, 4
	s_mul_i32 s37, s36, s5
	s_add_i32 s37, s37, s6
	s_min_u32 s37, s37, 0x3fff
	s_lshl_b32 s37, s37, 9
	s_add_u32 s82, s12, s37
	s_addc_u32 s83, s13, 0
	v_lshlrev_b32_e32 v219, 2, v228
	global_load_dword v104, v219, s[82:83]
	global_load_dword v105, v219, s[82:83] offset:256
	s_movk_i32 s36, 5
	s_mul_i32 s37, s36, s5
	s_add_i32 s37, s37, s6
	s_min_u32 s37, s37, 0x3fff
	s_lshl_b32 s37, s37, 9
	s_add_u32 s82, s12, s37
	s_addc_u32 s83, s13, 0
	v_lshlrev_b32_e32 v219, 2, v228
	global_load_dword v106, v219, s[82:83]
	global_load_dword v107, v219, s[82:83] offset:256
	s_movk_i32 s36, 6
	s_mul_i32 s37, s36, s5
	s_add_i32 s37, s37, s6
	s_min_u32 s37, s37, 0x3fff
	s_lshl_b32 s37, s37, 9
	s_add_u32 s82, s12, s37
	s_addc_u32 s83, s13, 0
	v_lshlrev_b32_e32 v219, 2, v228
	global_load_dword v108, v219, s[82:83]
	global_load_dword v109, v219, s[82:83] offset:256
	s_movk_i32 s36, 7
	s_mul_i32 s37, s36, s5
	s_add_i32 s37, s37, s6
	s_min_u32 s37, s37, 0x3fff
	s_lshl_b32 s37, s37, 9
	s_add_u32 s82, s12, s37
	s_addc_u32 s83, s13, 0
	v_lshlrev_b32_e32 v219, 2, v228
	global_load_dword v110, v219, s[82:83]
	global_load_dword v111, v219, s[82:83] offset:256
	s_waitcnt vmcnt(0)
	ds_write_b32 v230, v96 offset:0
	ds_write_b32 v230, v97 offset:256
	ds_write_b32 v230, v98 offset:512
	ds_write_b32 v230, v99 offset:768
	ds_write_b32 v230, v100 offset:1024
	ds_write_b32 v230, v101 offset:1280
	ds_write_b32 v230, v102 offset:1536
	ds_write_b32 v230, v103 offset:1792
	ds_write_b32 v230, v104 offset:2048
	ds_write_b32 v230, v105 offset:2304
	ds_write_b32 v230, v106 offset:2560
	ds_write_b32 v230, v107 offset:2816
	ds_write_b32 v230, v108 offset:3072
	ds_write_b32 v230, v109 offset:3328
	ds_write_b32 v230, v110 offset:3584
	ds_write_b32 v230, v111 offset:3840
	s_waitcnt lgkmcnt(0)
	s_mov_b32 s8, 0
	s_mov_b32 s7, 0
	s_mov_b32 s54, 0
	s_mov_b32 s53, 0
	s_mul_i32 s55, s53, s5
	s_add_i32 s55, s55, s6
	s_min_u32 s55, s55, 0x3fff
	s_and_b32 s34, s54, 7
	s_mul_i32 s34, s34, 0x300000
	s_cmp_lt_u32 s54, 8
	s_cselect_b32 s30, s16, s18
	s_cselect_b32 s31, s17, s19
	s_add_u32 s30, s30, s34
	s_addc_u32 s31, s31, 0
	s_and_b32 s34, s54, 7
	s_lshl_b32 s34, s34, 6
	s_lshl_b32 s35, s55, 12
	s_add_u32 s34, s34, s35
	s_add_u32 s32, s10, s34
	s_addc_u32 s33, s11, 0
	s_lshl_b32 s34, s53, 9
	v_add_u32_e32 v216, s34, v223
	ds_read_b128 v[80:83], v216 offset:0
	ds_read_b128 v[84:87], v216 offset:16
	ds_read_b128 v[88:91], v216 offset:32
	ds_read_b128 v[92:95], v216 offset:48
	s_waitcnt lgkmcnt(0)
	global_load_dwordx2 v[64:65], v224, s[32:33] offset:0
	global_load_dwordx2 v[66:67], v224, s[32:33] offset:512
	global_load_dwordx2 v[68:69], v224, s[32:33] offset:1024
	global_load_dwordx2 v[70:71], v224, s[32:33] offset:1536
	global_load_dwordx2 v[72:73], v224, s[32:33] offset:2048
	global_load_dwordx2 v[74:75], v224, s[32:33] offset:2560
	global_load_dwordx2 v[76:77], v224, s[32:33] offset:3072
	global_load_dwordx2 v[78:79], v224, s[32:33] offset:3584
	v_mad_u32_u24 v217, v80, s52, v220
	v_add_u32_e32 v218, v217, v221
	global_load_dwordx4 v[96:99], v217, s[30:31]
	global_load_dwordx2 v[100:101], v218, s[30:31]
	v_mad_u32_u24 v217, v81, s52, v220
	v_add_u32_e32 v218, v217, v221
	global_load_dwordx4 v[102:105], v217, s[30:31]
	global_load_dwordx2 v[106:107], v218, s[30:31]
	v_mad_u32_u24 v217, v82, s52, v220
	v_add_u32_e32 v218, v217, v221
	global_load_dwordx4 v[108:111], v217, s[30:31]
	global_load_dwordx2 v[112:113], v218, s[30:31]
	v_mad_u32_u24 v217, v83, s52, v220
	v_add_u32_e32 v218, v217, v221
	global_load_dwordx4 v[114:117], v217, s[30:31]
	global_load_dwordx2 v[118:119], v218, s[30:31]
	v_mad_u32_u24 v217, v84, s52, v220
	v_add_u32_e32 v218, v217, v221
	global_load_dwordx4 v[120:123], v217, s[30:31]
	global_load_dwordx2 v[124:125], v218, s[30:31]
	v_mad_u32_u24 v217, v85, s52, v220
	v_add_u32_e32 v218, v217, v221
	global_load_dwordx4 v[126:129], v217, s[30:31]
	global_load_dwordx2 v[130:131], v218, s[30:31]
	v_mad_u32_u24 v217, v86, s52, v220
	v_add_u32_e32 v218, v217, v221
	global_load_dwordx4 v[132:135], v217, s[30:31]
	global_load_dwordx2 v[136:137], v218, s[30:31]
	v_mad_u32_u24 v217, v87, s52, v220
	v_add_u32_e32 v218, v217, v221
	global_load_dwordx4 v[138:141], v217, s[30:31]
	global_load_dwordx2 v[142:143], v218, s[30:31]
	v_mad_u32_u24 v217, v88, s52, v220
	v_add_u32_e32 v218, v217, v221
	global_load_dwordx4 v[144:147], v217, s[30:31]
	global_load_dwordx2 v[148:149], v218, s[30:31]
	v_mad_u32_u24 v217, v89, s52, v220
	v_add_u32_e32 v218, v217, v221
	global_load_dwordx4 v[150:153], v217, s[30:31]
	global_load_dwordx2 v[154:155], v218, s[30:31]
	v_mad_u32_u24 v217, v90, s52, v220
	v_add_u32_e32 v218, v217, v221
	global_load_dwordx4 v[156:159], v217, s[30:31]
	global_load_dwordx2 v[160:161], v218, s[30:31]
	v_mad_u32_u24 v217, v91, s52, v220
	v_add_u32_e32 v218, v217, v221
	global_load_dwordx4 v[162:165], v217, s[30:31]
	global_load_dwordx2 v[166:167], v218, s[30:31]
	v_mad_u32_u24 v217, v92, s52, v220
	v_add_u32_e32 v218, v217, v221
	global_load_dwordx4 v[168:171], v217, s[30:31]
	global_load_dwordx2 v[172:173], v218, s[30:31]
	v_mad_u32_u24 v217, v93, s52, v220
	v_add_u32_e32 v218, v217, v221
	global_load_dwordx4 v[174:177], v217, s[30:31]
	global_load_dwordx2 v[178:179], v218, s[30:31]
	v_mad_u32_u24 v217, v94, s52, v220
	v_add_u32_e32 v218, v217, v221
	global_load_dwordx4 v[180:183], v217, s[30:31]
	global_load_dwordx2 v[184:185], v218, s[30:31]
	v_mad_u32_u24 v217, v95, s52, v220
	v_add_u32_e32 v218, v217, v221
	global_load_dwordx4 v[186:189], v217, s[30:31]
	global_load_dwordx2 v[190:191], v218, s[30:31]
.Lex_uloop:
	s_add_i32 s53, s7, 1
	s_mov_b32 s54, s8
	s_cmp_eq_u32 s53, 8
	s_cselect_b32 s53, 0, s53
	s_cselect_b32 s34, 1, 0
	s_add_i32 s54, s54, s34
	s_mul_i32 s55, s53, s5
	s_add_i32 s55, s55, s6
	s_min_u32 s55, s55, 0x3fff
	s_and_b32 s34, s54, 7
	s_mul_i32 s34, s34, 0x300000
	s_cmp_lt_u32 s54, 8
	s_cselect_b32 s30, s16, s18
	s_cselect_b32 s31, s17, s19
	s_add_u32 s30, s30, s34
	s_addc_u32 s31, s31, 0
	s_and_b32 s34, s54, 7
	s_lshl_b32 s34, s34, 6
	s_lshl_b32 s35, s55, 12
	s_add_u32 s34, s34, s35
	s_add_u32 s32, s10, s34
	s_addc_u32 s33, s11, 0
	s_lshl_b32 s34, s53, 9
	v_add_u32_e32 v216, s34, v223
	ds_read_b128 v[80:83], v216 offset:0
	ds_read_b128 v[84:87], v216 offset:16
	ds_read_b128 v[88:91], v216 offset:32
	ds_read_b128 v[92:95], v216 offset:48
	s_waitcnt vmcnt(32)
	v_lshlrev_b32_e32 v32, 16, v64
	v_and_b32_e32 v33, 0xffff0000, v64
	v_lshlrev_b32_e32 v34, 16, v65
	v_and_b32_e32 v35, 0xffff0000, v65
	v_lshlrev_b32_e32 v36, 16, v66
	v_and_b32_e32 v37, 0xffff0000, v66
	v_lshlrev_b32_e32 v38, 16, v67
	v_and_b32_e32 v39, 0xffff0000, v67
	v_lshlrev_b32_e32 v40, 16, v68
	v_and_b32_e32 v41, 0xffff0000, v68
	v_lshlrev_b32_e32 v42, 16, v69
	v_and_b32_e32 v43, 0xffff0000, v69
	v_lshlrev_b32_e32 v44, 16, v70
	v_and_b32_e32 v45, 0xffff0000, v70
	v_lshlrev_b32_e32 v46, 16, v71
	v_and_b32_e32 v47, 0xffff0000, v71
	v_lshlrev_b32_e32 v48, 16, v72
	v_and_b32_e32 v49, 0xffff0000, v72
	v_lshlrev_b32_e32 v50, 16, v73
	v_and_b32_e32 v51, 0xffff0000, v73
	v_lshlrev_b32_e32 v52, 16, v74
	v_and_b32_e32 v53, 0xffff0000, v74
	v_lshlrev_b32_e32 v54, 16, v75
	v_and_b32_e32 v55, 0xffff0000, v75
	v_lshlrev_b32_e32 v56, 16, v76
	v_and_b32_e32 v57, 0xffff0000, v76
	v_lshlrev_b32_e32 v58, 16, v77
	v_and_b32_e32 v59, 0xffff0000, v77
	v_lshlrev_b32_e32 v60, 16, v78
	v_and_b32_e32 v61, 0xffff0000, v78
	v_lshlrev_b32_e32 v62, 16, v79
	v_and_b32_e32 v63, 0xffff0000, v79
	s_waitcnt vmcnt(30)
	v_cvt_scalef32_pk32_f32_fp6 v[0:31], v[96:101], 1.0
	v_pk_mul_f32 v[208:209], v[0:1], v[32:33]
	v_pk_mul_f32 v[210:211], v[2:3], v[34:35]
	v_pk_fma_f32 v[208:209], v[4:5], v[36:37], v[208:209]
	v_pk_fma_f32 v[210:211], v[6:7], v[38:39], v[210:211]
	v_pk_fma_f32 v[208:209], v[8:9], v[40:41], v[208:209]
	v_pk_fma_f32 v[210:211], v[10:11], v[42:43], v[210:211]
	v_pk_fma_f32 v[208:209], v[12:13], v[44:45], v[208:209]
	v_pk_fma_f32 v[210:211], v[14:15], v[46:47], v[210:211]
	v_pk_fma_f32 v[208:209], v[16:17], v[48:49], v[208:209]
	v_pk_fma_f32 v[210:211], v[18:19], v[50:51], v[210:211]
	v_pk_fma_f32 v[208:209], v[20:21], v[52:53], v[208:209]
	v_pk_fma_f32 v[210:211], v[22:23], v[54:55], v[210:211]
	v_pk_fma_f32 v[208:209], v[24:25], v[56:57], v[208:209]
	v_pk_fma_f32 v[210:211], v[26:27], v[58:59], v[210:211]
	v_pk_fma_f32 v[208:209], v[28:29], v[60:61], v[208:209]
	v_pk_fma_f32 v[210:211], v[30:31], v[62:63], v[210:211]
	v_pk_add_f32 v[208:209], v[208:209], v[210:211]
	v_add_f32_e32 v192, v208, v209
	s_waitcnt vmcnt(28)
	v_cvt_scalef32_pk32_f32_fp6 v[0:31], v[102:107], 1.0
	v_pk_mul_f32 v[208:209], v[0:1], v[32:33]
	v_pk_mul_f32 v[210:211], v[2:3], v[34:35]
	v_pk_fma_f32 v[208:209], v[4:5], v[36:37], v[208:209]
	v_pk_fma_f32 v[210:211], v[6:7], v[38:39], v[210:211]
	v_pk_fma_f32 v[208:209], v[8:9], v[40:41], v[208:209]
	v_pk_fma_f32 v[210:211], v[10:11], v[42:43], v[210:211]
	v_pk_fma_f32 v[208:209], v[12:13], v[44:45], v[208:209]
	v_pk_fma_f32 v[210:211], v[14:15], v[46:47], v[210:211]
	v_pk_fma_f32 v[208:209], v[16:17], v[48:49], v[208:209]
	v_pk_fma_f32 v[210:211], v[18:19], v[50:51], v[210:211]
	v_pk_fma_f32 v[208:209], v[20:21], v[52:53], v[208:209]
	v_pk_fma_f32 v[210:211], v[22:23], v[54:55], v[210:211]
	v_pk_fma_f32 v[208:209], v[24:25], v[56:57], v[208:209]
	v_pk_fma_f32 v[210:211], v[26:27], v[58:59], v[210:211]
	v_pk_fma_f32 v[208:209], v[28:29], v[60:61], v[208:209]
	v_pk_fma_f32 v[210:211], v[30:31], v[62:63], v[210:211]
	v_pk_add_f32 v[208:209], v[208:209], v[210:211]
	v_add_f32_e32 v193, v208, v209
	s_waitcnt vmcnt(26)
	v_cvt_scalef32_pk32_f32_fp6 v[0:31], v[108:113], 1.0
	v_pk_mul_f32 v[208:209], v[0:1], v[32:33]
	v_pk_mul_f32 v[210:211], v[2:3], v[34:35]
	v_pk_fma_f32 v[208:209], v[4:5], v[36:37], v[208:209]
	v_pk_fma_f32 v[210:211], v[6:7], v[38:39], v[210:211]
	v_pk_fma_f32 v[208:209], v[8:9], v[40:41], v[208:209]
	v_pk_fma_f32 v[210:211], v[10:11], v[42:43], v[210:211]
	v_pk_fma_f32 v[208:209], v[12:13], v[44:45], v[208:209]
	v_pk_fma_f32 v[210:211], v[14:15], v[46:47], v[210:211]
	v_pk_fma_f32 v[208:209], v[16:17], v[48:49], v[208:209]
	v_pk_fma_f32 v[210:211], v[18:19], v[50:51], v[210:211]
	v_pk_fma_f32 v[208:209], v[20:21], v[52:53], v[208:209]
	v_pk_fma_f32 v[210:211], v[22:23], v[54:55], v[210:211]
	v_pk_fma_f32 v[208:209], v[24:25], v[56:57], v[208:209]
	v_pk_fma_f32 v[210:211], v[26:27], v[58:59], v[210:211]
	v_pk_fma_f32 v[208:209], v[28:29], v[60:61], v[208:209]
	v_pk_fma_f32 v[210:211], v[30:31], v[62:63], v[210:211]
	v_pk_add_f32 v[208:209], v[208:209], v[210:211]
	v_add_f32_e32 v194, v208, v209
	s_waitcnt vmcnt(24)
	v_cvt_scalef32_pk32_f32_fp6 v[0:31], v[114:119], 1.0
	v_pk_mul_f32 v[208:209], v[0:1], v[32:33]
	v_pk_mul_f32 v[210:211], v[2:3], v[34:35]
	v_pk_fma_f32 v[208:209], v[4:5], v[36:37], v[208:209]
	v_pk_fma_f32 v[210:211], v[6:7], v[38:39], v[210:211]
	v_pk_fma_f32 v[208:209], v[8:9], v[40:41], v[208:209]
	v_pk_fma_f32 v[210:211], v[10:11], v[42:43], v[210:211]
	v_pk_fma_f32 v[208:209], v[12:13], v[44:45], v[208:209]
	v_pk_fma_f32 v[210:211], v[14:15], v[46:47], v[210:211]
	v_pk_fma_f32 v[208:209], v[16:17], v[48:49], v[208:209]
	v_pk_fma_f32 v[210:211], v[18:19], v[50:51], v[210:211]
	v_pk_fma_f32 v[208:209], v[20:21], v[52:53], v[208:209]
	v_pk_fma_f32 v[210:211], v[22:23], v[54:55], v[210:211]
	v_pk_fma_f32 v[208:209], v[24:25], v[56:57], v[208:209]
	v_pk_fma_f32 v[210:211], v[26:27], v[58:59], v[210:211]
	v_pk_fma_f32 v[208:209], v[28:29], v[60:61], v[208:209]
	v_pk_fma_f32 v[210:211], v[30:31], v[62:63], v[210:211]
	v_pk_add_f32 v[208:209], v[208:209], v[210:211]
	v_add_f32_e32 v195, v208, v209
	s_waitcnt vmcnt(22)
	v_cvt_scalef32_pk32_f32_fp6 v[0:31], v[120:125], 1.0
	v_pk_mul_f32 v[208:209], v[0:1], v[32:33]
	v_pk_mul_f32 v[210:211], v[2:3], v[34:35]
	v_pk_fma_f32 v[208:209], v[4:5], v[36:37], v[208:209]
	v_pk_fma_f32 v[210:211], v[6:7], v[38:39], v[210:211]
	v_pk_fma_f32 v[208:209], v[8:9], v[40:41], v[208:209]
	v_pk_fma_f32 v[210:211], v[10:11], v[42:43], v[210:211]
	v_pk_fma_f32 v[208:209], v[12:13], v[44:45], v[208:209]
	v_pk_fma_f32 v[210:211], v[14:15], v[46:47], v[210:211]
	v_pk_fma_f32 v[208:209], v[16:17], v[48:49], v[208:209]
	v_pk_fma_f32 v[210:211], v[18:19], v[50:51], v[210:211]
	v_pk_fma_f32 v[208:209], v[20:21], v[52:53], v[208:209]
	v_pk_fma_f32 v[210:211], v[22:23], v[54:55], v[210:211]
	v_pk_fma_f32 v[208:209], v[24:25], v[56:57], v[208:209]
	v_pk_fma_f32 v[210:211], v[26:27], v[58:59], v[210:211]
	v_pk_fma_f32 v[208:209], v[28:29], v[60:61], v[208:209]
	v_pk_fma_f32 v[210:211], v[30:31], v[62:63], v[210:211]
	v_pk_add_f32 v[208:209], v[208:209], v[210:211]
	v_add_f32_e32 v196, v208, v209
	s_waitcnt vmcnt(20)
	v_cvt_scalef32_pk32_f32_fp6 v[0:31], v[126:131], 1.0
	v_pk_mul_f32 v[208:209], v[0:1], v[32:33]
	v_pk_mul_f32 v[210:211], v[2:3], v[34:35]
	v_pk_fma_f32 v[208:209], v[4:5], v[36:37], v[208:209]
	v_pk_fma_f32 v[210:211], v[6:7], v[38:39], v[210:211]
	v_pk_fma_f32 v[208:209], v[8:9], v[40:41], v[208:209]
	v_pk_fma_f32 v[210:211], v[10:11], v[42:43], v[210:211]
	v_pk_fma_f32 v[208:209], v[12:13], v[44:45], v[208:209]
	v_pk_fma_f32 v[210:211], v[14:15], v[46:47], v[210:211]
	v_pk_fma_f32 v[208:209], v[16:17], v[48:49], v[208:209]
	v_pk_fma_f32 v[210:211], v[18:19], v[50:51], v[210:211]
	v_pk_fma_f32 v[208:209], v[20:21], v[52:53], v[208:209]
	v_pk_fma_f32 v[210:211], v[22:23], v[54:55], v[210:211]
	v_pk_fma_f32 v[208:209], v[24:25], v[56:57], v[208:209]
	v_pk_fma_f32 v[210:211], v[26:27], v[58:59], v[210:211]
	v_pk_fma_f32 v[208:209], v[28:29], v[60:61], v[208:209]
	v_pk_fma_f32 v[210:211], v[30:31], v[62:63], v[210:211]
	v_pk_add_f32 v[208:209], v[208:209], v[210:211]
	v_add_f32_e32 v197, v208, v209
	s_waitcnt vmcnt(18)
	v_cvt_scalef32_pk32_f32_fp6 v[0:31], v[132:137], 1.0
	v_pk_mul_f32 v[208:209], v[0:1], v[32:33]
	v_pk_mul_f32 v[210:211], v[2:3], v[34:35]
	v_pk_fma_f32 v[208:209], v[4:5], v[36:37], v[208:209]
	v_pk_fma_f32 v[210:211], v[6:7], v[38:39], v[210:211]
	v_pk_fma_f32 v[208:209], v[8:9], v[40:41], v[208:209]
	v_pk_fma_f32 v[210:211], v[10:11], v[42:43], v[210:211]
	v_pk_fma_f32 v[208:209], v[12:13], v[44:45], v[208:209]
	v_pk_fma_f32 v[210:211], v[14:15], v[46:47], v[210:211]
	v_pk_fma_f32 v[208:209], v[16:17], v[48:49], v[208:209]
	v_pk_fma_f32 v[210:211], v[18:19], v[50:51], v[210:211]
	v_pk_fma_f32 v[208:209], v[20:21], v[52:53], v[208:209]
	v_pk_fma_f32 v[210:211], v[22:23], v[54:55], v[210:211]
	v_pk_fma_f32 v[208:209], v[24:25], v[56:57], v[208:209]
	v_pk_fma_f32 v[210:211], v[26:27], v[58:59], v[210:211]
	v_pk_fma_f32 v[208:209], v[28:29], v[60:61], v[208:209]
	v_pk_fma_f32 v[210:211], v[30:31], v[62:63], v[210:211]
	v_pk_add_f32 v[208:209], v[208:209], v[210:211]
	v_add_f32_e32 v198, v208, v209
	s_waitcnt vmcnt(16)
	v_cvt_scalef32_pk32_f32_fp6 v[0:31], v[138:143], 1.0
	v_pk_mul_f32 v[208:209], v[0:1], v[32:33]
	v_pk_mul_f32 v[210:211], v[2:3], v[34:35]
	v_pk_fma_f32 v[208:209], v[4:5], v[36:37], v[208:209]
	v_pk_fma_f32 v[210:211], v[6:7], v[38:39], v[210:211]
	v_pk_fma_f32 v[208:209], v[8:9], v[40:41], v[208:209]
	v_pk_fma_f32 v[210:211], v[10:11], v[42:43], v[210:211]
	v_pk_fma_f32 v[208:209], v[12:13], v[44:45], v[208:209]
	v_pk_fma_f32 v[210:211], v[14:15], v[46:47], v[210:211]
	v_pk_fma_f32 v[208:209], v[16:17], v[48:49], v[208:209]
	v_pk_fma_f32 v[210:211], v[18:19], v[50:51], v[210:211]
	v_pk_fma_f32 v[208:209], v[20:21], v[52:53], v[208:209]
	v_pk_fma_f32 v[210:211], v[22:23], v[54:55], v[210:211]
	v_pk_fma_f32 v[208:209], v[24:25], v[56:57], v[208:209]
	v_pk_fma_f32 v[210:211], v[26:27], v[58:59], v[210:211]
	v_pk_fma_f32 v[208:209], v[28:29], v[60:61], v[208:209]
	v_pk_fma_f32 v[210:211], v[30:31], v[62:63], v[210:211]
	v_pk_add_f32 v[208:209], v[208:209], v[210:211]
	v_add_f32_e32 v199, v208, v209
	s_waitcnt lgkmcnt(0)
	global_load_dwordx2 v[64:65], v224, s[32:33] offset:0
	global_load_dwordx2 v[66:67], v224, s[32:33] offset:512
	global_load_dwordx2 v[68:69], v224, s[32:33] offset:1024
	global_load_dwordx2 v[70:71], v224, s[32:33] offset:1536
	global_load_dwordx2 v[72:73], v224, s[32:33] offset:2048
	global_load_dwordx2 v[74:75], v224, s[32:33] offset:2560
	global_load_dwordx2 v[76:77], v224, s[32:33] offset:3072
	global_load_dwordx2 v[78:79], v224, s[32:33] offset:3584
	v_mad_u32_u24 v217, v80, s52, v220
	v_add_u32_e32 v218, v217, v221
	global_load_dwordx4 v[96:99], v217, s[30:31]
	global_load_dwordx2 v[100:101], v218, s[30:31]
	v_mad_u32_u24 v217, v81, s52, v220
	v_add_u32_e32 v218, v217, v221
	global_load_dwordx4 v[102:105], v217, s[30:31]
	global_load_dwordx2 v[106:107], v218, s[30:31]
	v_mad_u32_u24 v217, v82, s52, v220
	v_add_u32_e32 v218, v217, v221
	global_load_dwordx4 v[108:111], v217, s[30:31]
	global_load_dwordx2 v[112:113], v218, s[30:31]
	v_mad_u32_u24 v217, v83, s52, v220
	v_add_u32_e32 v218, v217, v221
	global_load_dwordx4 v[114:117], v217, s[30:31]
	global_load_dwordx2 v[118:119], v218, s[30:31]
	v_mad_u32_u24 v217, v84, s52, v220
	v_add_u32_e32 v218, v217, v221
	global_load_dwordx4 v[120:123], v217, s[30:31]
	global_load_dwordx2 v[124:125], v218, s[30:31]
	v_mad_u32_u24 v217, v85, s52, v220
	v_add_u32_e32 v218, v217, v221
	global_load_dwordx4 v[126:129], v217, s[30:31]
	global_load_dwordx2 v[130:131], v218, s[30:31]
	v_mad_u32_u24 v217, v86, s52, v220
	v_add_u32_e32 v218, v217, v221
	global_load_dwordx4 v[132:135], v217, s[30:31]
	global_load_dwordx2 v[136:137], v218, s[30:31]
	v_mad_u32_u24 v217, v87, s52, v220
	v_add_u32_e32 v218, v217, v221
	global_load_dwordx4 v[138:141], v217, s[30:31]
	global_load_dwordx2 v[142:143], v218, s[30:31]
	s_waitcnt vmcnt(38)
	v_cvt_scalef32_pk32_f32_fp6 v[0:31], v[144:149], 1.0
	v_pk_mul_f32 v[208:209], v[0:1], v[32:33]
	v_pk_mul_f32 v[210:211], v[2:3], v[34:35]
	v_pk_fma_f32 v[208:209], v[4:5], v[36:37], v[208:209]
	v_pk_fma_f32 v[210:211], v[6:7], v[38:39], v[210:211]
	v_pk_fma_f32 v[208:209], v[8:9], v[40:41], v[208:209]
	v_pk_fma_f32 v[210:211], v[10:11], v[42:43], v[210:211]
	v_pk_fma_f32 v[208:209], v[12:13], v[44:45], v[208:209]
	v_pk_fma_f32 v[210:211], v[14:15], v[46:47], v[210:211]
	v_pk_fma_f32 v[208:209], v[16:17], v[48:49], v[208:209]
	v_pk_fma_f32 v[210:211], v[18:19], v[50:51], v[210:211]
	v_pk_fma_f32 v[208:209], v[20:21], v[52:53], v[208:209]
	v_pk_fma_f32 v[210:211], v[22:23], v[54:55], v[210:211]
	v_pk_fma_f32 v[208:209], v[24:25], v[56:57], v[208:209]
	v_pk_fma_f32 v[210:211], v[26:27], v[58:59], v[210:211]
	v_pk_fma_f32 v[208:209], v[28:29], v[60:61], v[208:209]
	v_pk_fma_f32 v[210:211], v[30:31], v[62:63], v[210:211]
	v_pk_add_f32 v[208:209], v[208:209], v[210:211]
	v_add_f32_e32 v200, v208, v209
	s_waitcnt vmcnt(36)
	v_cvt_scalef32_pk32_f32_fp6 v[0:31], v[150:155], 1.0
	v_pk_mul_f32 v[208:209], v[0:1], v[32:33]
	v_pk_mul_f32 v[210:211], v[2:3], v[34:35]
	v_pk_fma_f32 v[208:209], v[4:5], v[36:37], v[208:209]
	v_pk_fma_f32 v[210:211], v[6:7], v[38:39], v[210:211]
	v_pk_fma_f32 v[208:209], v[8:9], v[40:41], v[208:209]
	v_pk_fma_f32 v[210:211], v[10:11], v[42:43], v[210:211]
	v_pk_fma_f32 v[208:209], v[12:13], v[44:45], v[208:209]
	v_pk_fma_f32 v[210:211], v[14:15], v[46:47], v[210:211]
	v_pk_fma_f32 v[208:209], v[16:17], v[48:49], v[208:209]
	v_pk_fma_f32 v[210:211], v[18:19], v[50:51], v[210:211]
	v_pk_fma_f32 v[208:209], v[20:21], v[52:53], v[208:209]
	v_pk_fma_f32 v[210:211], v[22:23], v[54:55], v[210:211]
	v_pk_fma_f32 v[208:209], v[24:25], v[56:57], v[208:209]
	v_pk_fma_f32 v[210:211], v[26:27], v[58:59], v[210:211]
	v_pk_fma_f32 v[208:209], v[28:29], v[60:61], v[208:209]
	v_pk_fma_f32 v[210:211], v[30:31], v[62:63], v[210:211]
	v_pk_add_f32 v[208:209], v[208:209], v[210:211]
	v_add_f32_e32 v201, v208, v209
	s_waitcnt vmcnt(34)
	v_cvt_scalef32_pk32_f32_fp6 v[0:31], v[156:161], 1.0
	v_pk_mul_f32 v[208:209], v[0:1], v[32:33]
	v_pk_mul_f32 v[210:211], v[2:3], v[34:35]
	v_pk_fma_f32 v[208:209], v[4:5], v[36:37], v[208:209]
	v_pk_fma_f32 v[210:211], v[6:7], v[38:39], v[210:211]
	v_pk_fma_f32 v[208:209], v[8:9], v[40:41], v[208:209]
	v_pk_fma_f32 v[210:211], v[10:11], v[42:43], v[210:211]
	v_pk_fma_f32 v[208:209], v[12:13], v[44:45], v[208:209]
	v_pk_fma_f32 v[210:211], v[14:15], v[46:47], v[210:211]
	v_pk_fma_f32 v[208:209], v[16:17], v[48:49], v[208:209]
	v_pk_fma_f32 v[210:211], v[18:19], v[50:51], v[210:211]
	v_pk_fma_f32 v[208:209], v[20:21], v[52:53], v[208:209]
	v_pk_fma_f32 v[210:211], v[22:23], v[54:55], v[210:211]
	v_pk_fma_f32 v[208:209], v[24:25], v[56:57], v[208:209]
	v_pk_fma_f32 v[210:211], v[26:27], v[58:59], v[210:211]
	v_pk_fma_f32 v[208:209], v[28:29], v[60:61], v[208:209]
	v_pk_fma_f32 v[210:211], v[30:31], v[62:63], v[210:211]
	v_pk_add_f32 v[208:209], v[208:209], v[210:211]
	v_add_f32_e32 v202, v208, v209
	s_waitcnt vmcnt(32)
	v_cvt_scalef32_pk32_f32_fp6 v[0:31], v[162:167], 1.0
	v_pk_mul_f32 v[208:209], v[0:1], v[32:33]
	v_pk_mul_f32 v[210:211], v[2:3], v[34:35]
	v_pk_fma_f32 v[208:209], v[4:5], v[36:37], v[208:209]
	v_pk_fma_f32 v[210:211], v[6:7], v[38:39], v[210:211]
	v_pk_fma_f32 v[208:209], v[8:9], v[40:41], v[208:209]
	v_pk_fma_f32 v[210:211], v[10:11], v[42:43], v[210:211]
	v_pk_fma_f32 v[208:209], v[12:13], v[44:45], v[208:209]
	v_pk_fma_f32 v[210:211], v[14:15], v[46:47], v[210:211]
	v_pk_fma_f32 v[208:209], v[16:17], v[48:49], v[208:209]
	v_pk_fma_f32 v[210:211], v[18:19], v[50:51], v[210:211]
	v_pk_fma_f32 v[208:209], v[20:21], v[52:53], v[208:209]
	v_pk_fma_f32 v[210:211], v[22:23], v[54:55], v[210:211]
	v_pk_fma_f32 v[208:209], v[24:25], v[56:57], v[208:209]
	v_pk_fma_f32 v[210:211], v[26:27], v[58:59], v[210:211]
	v_pk_fma_f32 v[208:209], v[28:29], v[60:61], v[208:209]
	v_pk_fma_f32 v[210:211], v[30:31], v[62:63], v[210:211]
	v_pk_add_f32 v[208:209], v[208:209], v[210:211]
	v_add_f32_e32 v203, v208, v209
	s_waitcnt vmcnt(30)
	v_cvt_scalef32_pk32_f32_fp6 v[0:31], v[168:173], 1.0
	v_pk_mul_f32 v[208:209], v[0:1], v[32:33]
	v_pk_mul_f32 v[210:211], v[2:3], v[34:35]
	v_pk_fma_f32 v[208:209], v[4:5], v[36:37], v[208:209]
	v_pk_fma_f32 v[210:211], v[6:7], v[38:39], v[210:211]
	v_pk_fma_f32 v[208:209], v[8:9], v[40:41], v[208:209]
	v_pk_fma_f32 v[210:211], v[10:11], v[42:43], v[210:211]
	v_pk_fma_f32 v[208:209], v[12:13], v[44:45], v[208:209]
	v_pk_fma_f32 v[210:211], v[14:15], v[46:47], v[210:211]
	v_pk_fma_f32 v[208:209], v[16:17], v[48:49], v[208:209]
	v_pk_fma_f32 v[210:211], v[18:19], v[50:51], v[210:211]
	v_pk_fma_f32 v[208:209], v[20:21], v[52:53], v[208:209]
	v_pk_fma_f32 v[210:211], v[22:23], v[54:55], v[210:211]
	v_pk_fma_f32 v[208:209], v[24:25], v[56:57], v[208:209]
	v_pk_fma_f32 v[210:211], v[26:27], v[58:59], v[210:211]
	v_pk_fma_f32 v[208:209], v[28:29], v[60:61], v[208:209]
	v_pk_fma_f32 v[210:211], v[30:31], v[62:63], v[210:211]
	v_pk_add_f32 v[208:209], v[208:209], v[210:211]
	v_add_f32_e32 v204, v208, v209
	s_waitcnt vmcnt(28)
	v_cvt_scalef32_pk32_f32_fp6 v[0:31], v[174:179], 1.0
	v_pk_mul_f32 v[208:209], v[0:1], v[32:33]
	v_pk_mul_f32 v[210:211], v[2:3], v[34:35]
	v_pk_fma_f32 v[208:209], v[4:5], v[36:37], v[208:209]
	v_pk_fma_f32 v[210:211], v[6:7], v[38:39], v[210:211]
	v_pk_fma_f32 v[208:209], v[8:9], v[40:41], v[208:209]
	v_pk_fma_f32 v[210:211], v[10:11], v[42:43], v[210:211]
	v_pk_fma_f32 v[208:209], v[12:13], v[44:45], v[208:209]
	v_pk_fma_f32 v[210:211], v[14:15], v[46:47], v[210:211]
	v_pk_fma_f32 v[208:209], v[16:17], v[48:49], v[208:209]
	v_pk_fma_f32 v[210:211], v[18:19], v[50:51], v[210:211]
	v_pk_fma_f32 v[208:209], v[20:21], v[52:53], v[208:209]
	v_pk_fma_f32 v[210:211], v[22:23], v[54:55], v[210:211]
	v_pk_fma_f32 v[208:209], v[24:25], v[56:57], v[208:209]
	v_pk_fma_f32 v[210:211], v[26:27], v[58:59], v[210:211]
	v_pk_fma_f32 v[208:209], v[28:29], v[60:61], v[208:209]
	v_pk_fma_f32 v[210:211], v[30:31], v[62:63], v[210:211]
	v_pk_add_f32 v[208:209], v[208:209], v[210:211]
	v_add_f32_e32 v205, v208, v209
	s_waitcnt vmcnt(26)
	v_cvt_scalef32_pk32_f32_fp6 v[0:31], v[180:185], 1.0
	v_pk_mul_f32 v[208:209], v[0:1], v[32:33]
	v_pk_mul_f32 v[210:211], v[2:3], v[34:35]
	v_pk_fma_f32 v[208:209], v[4:5], v[36:37], v[208:209]
	v_pk_fma_f32 v[210:211], v[6:7], v[38:39], v[210:211]
	v_pk_fma_f32 v[208:209], v[8:9], v[40:41], v[208:209]
	v_pk_fma_f32 v[210:211], v[10:11], v[42:43], v[210:211]
	v_pk_fma_f32 v[208:209], v[12:13], v[44:45], v[208:209]
	v_pk_fma_f32 v[210:211], v[14:15], v[46:47], v[210:211]
	v_pk_fma_f32 v[208:209], v[16:17], v[48:49], v[208:209]
	v_pk_fma_f32 v[210:211], v[18:19], v[50:51], v[210:211]
	v_pk_fma_f32 v[208:209], v[20:21], v[52:53], v[208:209]
	v_pk_fma_f32 v[210:211], v[22:23], v[54:55], v[210:211]
	v_pk_fma_f32 v[208:209], v[24:25], v[56:57], v[208:209]
	v_pk_fma_f32 v[210:211], v[26:27], v[58:59], v[210:211]
	v_pk_fma_f32 v[208:209], v[28:29], v[60:61], v[208:209]
	v_pk_fma_f32 v[210:211], v[30:31], v[62:63], v[210:211]
	v_pk_add_f32 v[208:209], v[208:209], v[210:211]
	v_add_f32_e32 v206, v208, v209
	s_waitcnt vmcnt(24)
	v_cvt_scalef32_pk32_f32_fp6 v[0:31], v[186:191], 1.0
	v_pk_mul_f32 v[208:209], v[0:1], v[32:33]
	v_pk_mul_f32 v[210:211], v[2:3], v[34:35]
	v_pk_fma_f32 v[208:209], v[4:5], v[36:37], v[208:209]
	v_pk_fma_f32 v[210:211], v[6:7], v[38:39], v[210:211]
	v_pk_fma_f32 v[208:209], v[8:9], v[40:41], v[208:209]
	v_pk_fma_f32 v[210:211], v[10:11], v[42:43], v[210:211]
	v_pk_fma_f32 v[208:209], v[12:13], v[44:45], v[208:209]
	v_pk_fma_f32 v[210:211], v[14:15], v[46:47], v[210:211]
	v_pk_fma_f32 v[208:209], v[16:17], v[48:49], v[208:209]
	v_pk_fma_f32 v[210:211], v[18:19], v[50:51], v[210:211]
	v_pk_fma_f32 v[208:209], v[20:21], v[52:53], v[208:209]
	v_pk_fma_f32 v[210:211], v[22:23], v[54:55], v[210:211]
	v_pk_fma_f32 v[208:209], v[24:25], v[56:57], v[208:209]
	v_pk_fma_f32 v[210:211], v[26:27], v[58:59], v[210:211]
	v_pk_fma_f32 v[208:209], v[28:29], v[60:61], v[208:209]
	v_pk_fma_f32 v[210:211], v[30:31], v[62:63], v[210:211]
	v_pk_add_f32 v[208:209], v[208:209], v[210:211]
	v_add_f32_e32 v207, v208, v209
	v_mad_u32_u24 v217, v88, s52, v220
	v_add_u32_e32 v218, v217, v221
	global_load_dwordx4 v[144:147], v217, s[30:31]
	global_load_dwordx2 v[148:149], v218, s[30:31]
	v_mad_u32_u24 v217, v89, s52, v220
	v_add_u32_e32 v218, v217, v221
	global_load_dwordx4 v[150:153], v217, s[30:31]
	global_load_dwordx2 v[154:155], v218, s[30:31]
	v_mad_u32_u24 v217, v90, s52, v220
	v_add_u32_e32 v218, v217, v221
	global_load_dwordx4 v[156:159], v217, s[30:31]
	global_load_dwordx2 v[160:161], v218, s[30:31]
	v_mad_u32_u24 v217, v91, s52, v220
	v_add_u32_e32 v218, v217, v221
	global_load_dwordx4 v[162:165], v217, s[30:31]
	global_load_dwordx2 v[166:167], v218, s[30:31]
	v_mad_u32_u24 v217, v92, s52, v220
	v_add_u32_e32 v218, v217, v221
	global_load_dwordx4 v[168:171], v217, s[30:31]
	global_load_dwordx2 v[172:173], v218, s[30:31]
	v_mad_u32_u24 v217, v93, s52, v220
	v_add_u32_e32 v218, v217, v221
	global_load_dwordx4 v[174:177], v217, s[30:31]
	global_load_dwordx2 v[178:179], v218, s[30:31]
	v_mad_u32_u24 v217, v94, s52, v220
	v_add_u32_e32 v218, v217, v221
	global_load_dwordx4 v[180:183], v217, s[30:31]
	global_load_dwordx2 v[184:185], v218, s[30:31]
	v_mad_u32_u24 v217, v95, s52, v220
	v_add_u32_e32 v218, v217, v221
	global_load_dwordx4 v[186:189], v217, s[30:31]
	global_load_dwordx2 v[190:191], v218, s[30:31]
	v_cndmask_b32_e64 v212, v200, v192, s[44:45]
	v_cndmask_b32_e64 v213, v192, v200, s[44:45]
	v_cndmask_b32_e64 v214, v201, v193, s[44:45]
	v_cndmask_b32_e64 v215, v193, v201, s[44:45]
	v_add_f32_dpp v192, v212, v213 row_half_mirror row_mask:0xf bank_mask:0xf
	v_add_f32_dpp v193, v214, v215 row_half_mirror row_mask:0xf bank_mask:0xf
	v_cndmask_b32_e64 v212, v202, v194, s[44:45]
	v_cndmask_b32_e64 v213, v194, v202, s[44:45]
	v_cndmask_b32_e64 v214, v203, v195, s[44:45]
	v_cndmask_b32_e64 v215, v195, v203, s[44:45]
	v_add_f32_dpp v194, v212, v213 row_half_mirror row_mask:0xf bank_mask:0xf
	v_add_f32_dpp v195, v214, v215 row_half_mirror row_mask:0xf bank_mask:0xf
	v_cndmask_b32_e64 v212, v204, v196, s[44:45]
	v_cndmask_b32_e64 v213, v196, v204, s[44:45]
	v_cndmask_b32_e64 v214, v205, v197, s[44:45]
	v_cndmask_b32_e64 v215, v197, v205, s[44:45]
	v_add_f32_dpp v196, v212, v213 row_half_mirror row_mask:0xf bank_mask:0xf
	v_add_f32_dpp v197, v214, v215 row_half_mirror row_mask:0xf bank_mask:0xf
	v_cndmask_b32_e64 v212, v206, v198, s[44:45]
	v_cndmask_b32_e64 v213, v198, v206, s[44:45]
	v_cndmask_b32_e64 v214, v207, v199, s[44:45]
	v_cndmask_b32_e64 v215, v199, v207, s[44:45]
	v_add_f32_dpp v198, v212, v213 row_half_mirror row_mask:0xf bank_mask:0xf
	v_add_f32_dpp v199, v214, v215 row_half_mirror row_mask:0xf bank_mask:0xf
	v_cndmask_b32_e64 v212, v196, v192, s[42:43]
	v_cndmask_b32_e64 v213, v192, v196, s[42:43]
	v_cndmask_b32_e64 v214, v197, v193, s[42:43]
	v_cndmask_b32_e64 v215, v193, v197, s[42:43]
	v_add_f32_dpp v192, v212, v213 quad_perm:[2,3,0,1] row_mask:0xf bank_mask:0xf
	v_add_f32_dpp v193, v214, v215 quad_perm:[2,3,0,1] row_mask:0xf bank_mask:0xf
	v_cndmask_b32_e64 v212, v198, v194, s[42:43]
	v_cndmask_b32_e64 v213, v194, v198, s[42:43]
	v_cndmask_b32_e64 v214, v199, v195, s[42:43]
	v_cndmask_b32_e64 v215, v195, v199, s[42:43]
	v_add_f32_dpp v194, v212, v213 quad_perm:[2,3,0,1] row_mask:0xf bank_mask:0xf
	v_add_f32_dpp v195, v214, v215 quad_perm:[2,3,0,1] row_mask:0xf bank_mask:0xf
	v_cndmask_b32_e64 v212, v194, v192, s[40:41]
	v_cndmask_b32_e64 v213, v192, v194, s[40:41]
	v_cndmask_b32_e64 v214, v195, v193, s[40:41]
	v_cndmask_b32_e64 v215, v193, v195, s[40:41]
	v_add_f32_dpp v192, v212, v213 quad_perm:[1,0,3,2] row_mask:0xf bank_mask:0xf
	v_add_f32_dpp v193, v214, v215 quad_perm:[1,0,3,2] row_mask:0xf bank_mask:0xf
	s_lshl_b32 s34, s7, 9
	s_addk_i32 s34, 0x1000
	v_add_u32_e32 v216, s34, v222
	s_cmp_eq_u32 s8, 0
	s_cbranch_scc1 .Lex_ufirst
	ds_read_b64 v[212:213], v216
	s_waitcnt lgkmcnt(0)
	v_pk_add_f32 v[192:193], v[192:193], v[212:213]
.Lex_ufirst:
	ds_write_b64 v216, v[192:193]
	s_mov_b32 s7, s53
	s_mov_b32 s8, s54
	s_cmp_lt_u32 s8, 8
	s_cbranch_scc1 .Lex_uloop
	s_waitcnt vmcnt(0) lgkmcnt(0)
	ds_read_b64 v[96:97], v222 offset:4096
	ds_read_b64 v[98:99], v222 offset:0
	ds_read_b64 v[108:109], v222 offset:4608
	ds_read_b64 v[110:111], v222 offset:512
	ds_read_b64 v[120:121], v222 offset:5120
	ds_read_b64 v[122:123], v222 offset:1024
	ds_read_b64 v[132:133], v222 offset:5632
	ds_read_b64 v[134:135], v222 offset:1536
	ds_read_b64 v[144:145], v222 offset:6144
	ds_read_b64 v[146:147], v222 offset:2048
	ds_read_b64 v[156:157], v222 offset:6656
	ds_read_b64 v[158:159], v222 offset:2560
	ds_read_b64 v[168:169], v222 offset:7168
	ds_read_b64 v[170:171], v222 offset:3072
	ds_read_b64 v[180:181], v222 offset:7680
	ds_read_b64 v[182:183], v222 offset:3584
	s_waitcnt lgkmcnt(0)
	s_movk_i32 s36, 0
	s_mul_i32 s37, s36, s5
	s_add_i32 s37, s37, s6
	s_min_u32 s37, s37, 0x3fff
	s_lshl_b32 s37, s37, 9
	s_add_u32 s82, s14, s37
	s_addc_u32 s83, s15, 0
	v_lshlrev_b32_e32 v219, 3, v228
	global_load_dwordx2 v[100:101], v219, s[82:83]
	v_lshlrev_b32_e32 v217, 2, v98
	v_lshlrev_b32_e32 v218, 2, v99
	global_load_dword v102, v217, s[20:21]
	global_load_dword v103, v218, s[20:21]
	global_load_dword v104, v217, s[22:23]
	global_load_dword v105, v218, s[22:23]
	s_movk_i32 s36, 1
	s_mul_i32 s37, s36, s5
	s_add_i32 s37, s37, s6
	s_min_u32 s37, s37, 0x3fff
	s_lshl_b32 s37, s37, 9
	s_add_u32 s82, s14, s37
	s_addc_u32 s83, s15, 0
	v_lshlrev_b32_e32 v219, 3, v228
	global_load_dwordx2 v[112:113], v219, s[82:83]
	v_lshlrev_b32_e32 v217, 2, v110
	v_lshlrev_b32_e32 v218, 2, v111
	global_load_dword v114, v217, s[20:21]
	global_load_dword v115, v218, s[20:21]
	global_load_dword v116, v217, s[22:23]
	global_load_dword v117, v218, s[22:23]
	s_movk_i32 s36, 2
	s_mul_i32 s37, s36, s5
	s_add_i32 s37, s37, s6
	s_min_u32 s37, s37, 0x3fff
	s_lshl_b32 s37, s37, 9
	s_add_u32 s82, s14, s37
	s_addc_u32 s83, s15, 0
	v_lshlrev_b32_e32 v219, 3, v228
	global_load_dwordx2 v[124:125], v219, s[82:83]
	v_lshlrev_b32_e32 v217, 2, v122
	v_lshlrev_b32_e32 v218, 2, v123
	global_load_dword v126, v217, s[20:21]
	global_load_dword v127, v218, s[20:21]
	global_load_dword v128, v217, s[22:23]
	global_load_dword v129, v218, s[22:23]
	s_movk_i32 s36, 3
	s_mul_i32 s37, s36, s5
	s_add_i32 s37, s37, s6
	s_min_u32 s37, s37, 0x3fff
	s_lshl_b32 s37, s37, 9
	s_add_u32 s82, s14, s37
	s_addc_u32 s83, s15, 0
	v_lshlrev_b32_e32 v219, 3, v228
	global_load_dwordx2 v[136:137], v219, s[82:83]
	v_lshlrev_b32_e32 v217, 2, v134
	v_lshlrev_b32_e32 v218, 2, v135
	global_load_dword v138, v217, s[20:21]
	global_load_dword v139, v218, s[20:21]
	global_load_dword v140, v217, s[22:23]
	global_load_dword v141, v218, s[22:23]
	s_movk_i32 s36, 4
	s_mul_i32 s37, s36, s5
	s_add_i32 s37, s37, s6
	s_min_u32 s37, s37, 0x3fff
	s_lshl_b32 s37, s37, 9
	s_add_u32 s82, s14, s37
	s_addc_u32 s83, s15, 0
	v_lshlrev_b32_e32 v219, 3, v228
	global_load_dwordx2 v[148:149], v219, s[82:83]
	v_lshlrev_b32_e32 v217, 2, v146
	v_lshlrev_b32_e32 v218, 2, v147
	global_load_dword v150, v217, s[20:21]
	global_load_dword v151, v218, s[20:21]
	global_load_dword v152, v217, s[22:23]
	global_load_dword v153, v218, s[22:23]
	s_movk_i32 s36, 5
	s_mul_i32 s37, s36, s5
	s_add_i32 s37, s37, s6
	s_min_u32 s37, s37, 0x3fff
	s_lshl_b32 s37, s37, 9
	s_add_u32 s82, s14, s37
	s_addc_u32 s83, s15, 0
	v_lshlrev_b32_e32 v219, 3, v228
	global_load_dwordx2 v[160:161], v219, s[82:83]
	v_lshlrev_b32_e32 v217, 2, v158
	v_lshlrev_b32_e32 v218, 2, v159
	global_load_dword v162, v217, s[20:21]
	global_load_dword v163, v218, s[20:21]
	global_load_dword v164, v217, s[22:23]
	global_load_dword v165, v218, s[22:23]
	s_movk_i32 s36, 6
	s_mul_i32 s37, s36, s5
	s_add_i32 s37, s37, s6
	s_min_u32 s37, s37, 0x3fff
	s_lshl_b32 s37, s37, 9
	s_add_u32 s82, s14, s37
	s_addc_u32 s83, s15, 0
	v_lshlrev_b32_e32 v219, 3, v228
	global_load_dwordx2 v[172:173], v219, s[82:83]
	v_lshlrev_b32_e32 v217, 2, v170
	v_lshlrev_b32_e32 v218, 2, v171
	global_load_dword v174, v217, s[20:21]
	global_load_dword v175, v218, s[20:21]
	global_load_dword v176, v217, s[22:23]
	global_load_dword v177, v218, s[22:23]
	s_movk_i32 s36, 7
	s_mul_i32 s37, s36, s5
	s_add_i32 s37, s37, s6
	s_min_u32 s37, s37, 0x3fff
	s_lshl_b32 s37, s37, 9
	s_add_u32 s82, s14, s37
	s_addc_u32 s83, s15, 0
	v_lshlrev_b32_e32 v219, 3, v228
	global_load_dwordx2 v[184:185], v219, s[82:83]
	v_lshlrev_b32_e32 v217, 2, v182
	v_lshlrev_b32_e32 v218, 2, v183
	global_load_dword v186, v217, s[20:21]
	global_load_dword v187, v218, s[20:21]
	global_load_dword v188, v217, s[22:23]
	global_load_dword v189, v218, s[22:23]
	s_waitcnt vmcnt(0)
	v_mul_f32_e32 v96, v102, v96
	v_mul_f32_e32 v0, 0x3f3504f3, v96
	v_mov_b32_e32 v6, s67
	v_fma_f32 v2, |v0|, s66, v6
	v_fma_f32 v2, |v0|, v2, s68
	v_fma_f32 v2, |v0|, v2, s69
	v_fma_f32 v2, |v0|, v2, s70
	v_fma_f32 v2, |v0|, v2, s71
	v_fma_f32 v2, |v0|, v2, s72
	v_fma_f32 v2, |v0|, v2, |v0|
	v_mul_f32_e32 v4, 0xbfb8aa3b, v2
	v_fma_f32 v5, v2, s73, -v4
	v_rndne_f32_e32 v6, v4
	v_fmac_f32_e32 v5, 0xb2a5705f, v2
	v_sub_f32_e32 v4, v4, v6
	v_add_f32_e32 v4, v4, v5
	v_cvt_i32_f32_e32 v5, v6
	v_exp_f32_e32 v4, v4
	v_cmp_nlt_f32_e64 s[82:83], s74, v2
	v_ldexp_f32 v4, v4, v5
	s_nop 0
	v_cndmask_b32_e64 v4, 0, v4, s[82:83]
	v_cmp_ngt_f32_e64 s[82:83], s75, v2
	v_mov_b32_e32 v6, 0x7f800000
	s_nop 0
	v_cndmask_b32_e64 v3, v6, v4, s[82:83]
	v_sub_f32_e32 v3, 1.0, v3
	v_mul_f32_e32 v4, v0, v0
	v_mov_b32_e32 v6, s76
	v_fmamk_f32 v5, v4, 0xba1345e1, v6
	v_fmaak_f32 v5, v4, v5, 0xbcdac9b8
	v_fmaak_f32 v5, v4, v5, 0x3de703be
	v_fmaak_f32 v5, v4, v5, 0xbec09330
	v_fmaak_f32 v4, v4, v5, 0x3e0375d0
	v_fma_f32 v7, |v0|, v4, |v0|
	v_cmp_nlt_f32_e64 s[82:83], |v0|, 1.0
	s_nop 1
	v_cndmask_b32_e64 v3, v7, v3, s[82:83]
	v_bfi_b32 v3, s77, v3, v0
	v_mul_f32_e32 v96, 0.5, v96
	v_add_f32_e32 v3, 1.0, v3
	v_mul_f32_e32 v96, v96, v3
	v_mul_f32_e32 v96, v96, v100
	v_mul_f32_e32 v96, v104, v96
	v_mul_f32_e32 v97, v103, v97
	v_mul_f32_e32 v0, 0x3f3504f3, v97
	v_mov_b32_e32 v6, s67
	v_fma_f32 v2, |v0|, s66, v6
	v_fma_f32 v2, |v0|, v2, s68
	v_fma_f32 v2, |v0|, v2, s69
	v_fma_f32 v2, |v0|, v2, s70
	v_fma_f32 v2, |v0|, v2, s71
	v_fma_f32 v2, |v0|, v2, s72
	v_fma_f32 v2, |v0|, v2, |v0|
	v_mul_f32_e32 v4, 0xbfb8aa3b, v2
	v_fma_f32 v5, v2, s73, -v4
	v_rndne_f32_e32 v6, v4
	v_fmac_f32_e32 v5, 0xb2a5705f, v2
	v_sub_f32_e32 v4, v4, v6
	v_add_f32_e32 v4, v4, v5
	v_cvt_i32_f32_e32 v5, v6
	v_exp_f32_e32 v4, v4
	v_cmp_nlt_f32_e64 s[82:83], s74, v2
	v_ldexp_f32 v4, v4, v5
	s_nop 0
	v_cndmask_b32_e64 v4, 0, v4, s[82:83]
	v_cmp_ngt_f32_e64 s[82:83], s75, v2
	v_mov_b32_e32 v6, 0x7f800000
	s_nop 0
	v_cndmask_b32_e64 v3, v6, v4, s[82:83]
	v_sub_f32_e32 v3, 1.0, v3
	v_mul_f32_e32 v4, v0, v0
	v_mov_b32_e32 v6, s76
	v_fmamk_f32 v5, v4, 0xba1345e1, v6
	v_fmaak_f32 v5, v4, v5, 0xbcdac9b8
	v_fmaak_f32 v5, v4, v5, 0x3de703be
	v_fmaak_f32 v5, v4, v5, 0xbec09330
	v_fmaak_f32 v4, v4, v5, 0x3e0375d0
	v_fma_f32 v7, |v0|, v4, |v0|
	v_cmp_nlt_f32_e64 s[82:83], |v0|, 1.0
	s_nop 1
	v_cndmask_b32_e64 v3, v7, v3, s[82:83]
	v_bfi_b32 v3, s77, v3, v0
	v_mul_f32_e32 v97, 0.5, v97
	v_add_f32_e32 v3, 1.0, v3
	v_mul_f32_e32 v97, v97, v3
	v_mul_f32_e32 v97, v97, v101
	v_mul_f32_e32 v97, v105, v97
	ds_write_b64 v222, v[96:97] offset:4096
	v_mul_f32_e32 v108, v114, v108
	v_mul_f32_e32 v0, 0x3f3504f3, v108
	v_mov_b32_e32 v6, s67
	v_fma_f32 v2, |v0|, s66, v6
	v_fma_f32 v2, |v0|, v2, s68
	v_fma_f32 v2, |v0|, v2, s69
	v_fma_f32 v2, |v0|, v2, s70
	v_fma_f32 v2, |v0|, v2, s71
	v_fma_f32 v2, |v0|, v2, s72
	v_fma_f32 v2, |v0|, v2, |v0|
	v_mul_f32_e32 v4, 0xbfb8aa3b, v2
	v_fma_f32 v5, v2, s73, -v4
	v_rndne_f32_e32 v6, v4
	v_fmac_f32_e32 v5, 0xb2a5705f, v2
	v_sub_f32_e32 v4, v4, v6
	v_add_f32_e32 v4, v4, v5
	v_cvt_i32_f32_e32 v5, v6
	v_exp_f32_e32 v4, v4
	v_cmp_nlt_f32_e64 s[82:83], s74, v2
	v_ldexp_f32 v4, v4, v5
	s_nop 0
	v_cndmask_b32_e64 v4, 0, v4, s[82:83]
	v_cmp_ngt_f32_e64 s[82:83], s75, v2
	v_mov_b32_e32 v6, 0x7f800000
	s_nop 0
	v_cndmask_b32_e64 v3, v6, v4, s[82:83]
	v_sub_f32_e32 v3, 1.0, v3
	v_mul_f32_e32 v4, v0, v0
	v_mov_b32_e32 v6, s76
	v_fmamk_f32 v5, v4, 0xba1345e1, v6
	v_fmaak_f32 v5, v4, v5, 0xbcdac9b8
	v_fmaak_f32 v5, v4, v5, 0x3de703be
	v_fmaak_f32 v5, v4, v5, 0xbec09330
	v_fmaak_f32 v4, v4, v5, 0x3e0375d0
	v_fma_f32 v7, |v0|, v4, |v0|
	v_cmp_nlt_f32_e64 s[82:83], |v0|, 1.0
	s_nop 1
	v_cndmask_b32_e64 v3, v7, v3, s[82:83]
	v_bfi_b32 v3, s77, v3, v0
	v_mul_f32_e32 v108, 0.5, v108
	v_add_f32_e32 v3, 1.0, v3
	v_mul_f32_e32 v108, v108, v3
	v_mul_f32_e32 v108, v108, v112
	v_mul_f32_e32 v108, v116, v108
	v_mul_f32_e32 v109, v115, v109
	v_mul_f32_e32 v0, 0x3f3504f3, v109
	v_mov_b32_e32 v6, s67
	v_fma_f32 v2, |v0|, s66, v6
	v_fma_f32 v2, |v0|, v2, s68
	v_fma_f32 v2, |v0|, v2, s69
	v_fma_f32 v2, |v0|, v2, s70
	v_fma_f32 v2, |v0|, v2, s71
	v_fma_f32 v2, |v0|, v2, s72
	v_fma_f32 v2, |v0|, v2, |v0|
	v_mul_f32_e32 v4, 0xbfb8aa3b, v2
	v_fma_f32 v5, v2, s73, -v4
	v_rndne_f32_e32 v6, v4
	v_fmac_f32_e32 v5, 0xb2a5705f, v2
	v_sub_f32_e32 v4, v4, v6
	v_add_f32_e32 v4, v4, v5
	v_cvt_i32_f32_e32 v5, v6
	v_exp_f32_e32 v4, v4
	v_cmp_nlt_f32_e64 s[82:83], s74, v2
	v_ldexp_f32 v4, v4, v5
	s_nop 0
	v_cndmask_b32_e64 v4, 0, v4, s[82:83]
	v_cmp_ngt_f32_e64 s[82:83], s75, v2
	v_mov_b32_e32 v6, 0x7f800000
	s_nop 0
	v_cndmask_b32_e64 v3, v6, v4, s[82:83]
	v_sub_f32_e32 v3, 1.0, v3
	v_mul_f32_e32 v4, v0, v0
	v_mov_b32_e32 v6, s76
	v_fmamk_f32 v5, v4, 0xba1345e1, v6
	v_fmaak_f32 v5, v4, v5, 0xbcdac9b8
	v_fmaak_f32 v5, v4, v5, 0x3de703be
	v_fmaak_f32 v5, v4, v5, 0xbec09330
	v_fmaak_f32 v4, v4, v5, 0x3e0375d0
	v_fma_f32 v7, |v0|, v4, |v0|
	v_cmp_nlt_f32_e64 s[82:83], |v0|, 1.0
	s_nop 1
	v_cndmask_b32_e64 v3, v7, v3, s[82:83]
	v_bfi_b32 v3, s77, v3, v0
	v_mul_f32_e32 v109, 0.5, v109
	v_add_f32_e32 v3, 1.0, v3
	v_mul_f32_e32 v109, v109, v3
	v_mul_f32_e32 v109, v109, v113
	v_mul_f32_e32 v109, v117, v109
	ds_write_b64 v222, v[108:109] offset:4608
	v_mul_f32_e32 v120, v126, v120
	v_mul_f32_e32 v0, 0x3f3504f3, v120
	v_mov_b32_e32 v6, s67
	v_fma_f32 v2, |v0|, s66, v6
	v_fma_f32 v2, |v0|, v2, s68
	v_fma_f32 v2, |v0|, v2, s69
	v_fma_f32 v2, |v0|, v2, s70
	v_fma_f32 v2, |v0|, v2, s71
	v_fma_f32 v2, |v0|, v2, s72
	v_fma_f32 v2, |v0|, v2, |v0|
	v_mul_f32_e32 v4, 0xbfb8aa3b, v2
	v_fma_f32 v5, v2, s73, -v4
	v_rndne_f32_e32 v6, v4
	v_fmac_f32_e32 v5, 0xb2a5705f, v2
	v_sub_f32_e32 v4, v4, v6
	v_add_f32_e32 v4, v4, v5
	v_cvt_i32_f32_e32 v5, v6
	v_exp_f32_e32 v4, v4
	v_cmp_nlt_f32_e64 s[82:83], s74, v2
	v_ldexp_f32 v4, v4, v5
	s_nop 0
	v_cndmask_b32_e64 v4, 0, v4, s[82:83]
	v_cmp_ngt_f32_e64 s[82:83], s75, v2
	v_mov_b32_e32 v6, 0x7f800000
	s_nop 0
	v_cndmask_b32_e64 v3, v6, v4, s[82:83]
	v_sub_f32_e32 v3, 1.0, v3
	v_mul_f32_e32 v4, v0, v0
	v_mov_b32_e32 v6, s76
	v_fmamk_f32 v5, v4, 0xba1345e1, v6
	v_fmaak_f32 v5, v4, v5, 0xbcdac9b8
	v_fmaak_f32 v5, v4, v5, 0x3de703be
	v_fmaak_f32 v5, v4, v5, 0xbec09330
	v_fmaak_f32 v4, v4, v5, 0x3e0375d0
	v_fma_f32 v7, |v0|, v4, |v0|
	v_cmp_nlt_f32_e64 s[82:83], |v0|, 1.0
	s_nop 1
	v_cndmask_b32_e64 v3, v7, v3, s[82:83]
	v_bfi_b32 v3, s77, v3, v0
	v_mul_f32_e32 v120, 0.5, v120
	v_add_f32_e32 v3, 1.0, v3
	v_mul_f32_e32 v120, v120, v3
	v_mul_f32_e32 v120, v120, v124
	v_mul_f32_e32 v120, v128, v120
	v_mul_f32_e32 v121, v127, v121
	v_mul_f32_e32 v0, 0x3f3504f3, v121
	v_mov_b32_e32 v6, s67
	v_fma_f32 v2, |v0|, s66, v6
	v_fma_f32 v2, |v0|, v2, s68
	v_fma_f32 v2, |v0|, v2, s69
	v_fma_f32 v2, |v0|, v2, s70
	v_fma_f32 v2, |v0|, v2, s71
	v_fma_f32 v2, |v0|, v2, s72
	v_fma_f32 v2, |v0|, v2, |v0|
	v_mul_f32_e32 v4, 0xbfb8aa3b, v2
	v_fma_f32 v5, v2, s73, -v4
	v_rndne_f32_e32 v6, v4
	v_fmac_f32_e32 v5, 0xb2a5705f, v2
	v_sub_f32_e32 v4, v4, v6
	v_add_f32_e32 v4, v4, v5
	v_cvt_i32_f32_e32 v5, v6
	v_exp_f32_e32 v4, v4
	v_cmp_nlt_f32_e64 s[82:83], s74, v2
	v_ldexp_f32 v4, v4, v5
	s_nop 0
	v_cndmask_b32_e64 v4, 0, v4, s[82:83]
	v_cmp_ngt_f32_e64 s[82:83], s75, v2
	v_mov_b32_e32 v6, 0x7f800000
	s_nop 0
	v_cndmask_b32_e64 v3, v6, v4, s[82:83]
	v_sub_f32_e32 v3, 1.0, v3
	v_mul_f32_e32 v4, v0, v0
	v_mov_b32_e32 v6, s76
	v_fmamk_f32 v5, v4, 0xba1345e1, v6
	v_fmaak_f32 v5, v4, v5, 0xbcdac9b8
	v_fmaak_f32 v5, v4, v5, 0x3de703be
	v_fmaak_f32 v5, v4, v5, 0xbec09330
	v_fmaak_f32 v4, v4, v5, 0x3e0375d0
	v_fma_f32 v7, |v0|, v4, |v0|
	v_cmp_nlt_f32_e64 s[82:83], |v0|, 1.0
	s_nop 1
	v_cndmask_b32_e64 v3, v7, v3, s[82:83]
	v_bfi_b32 v3, s77, v3, v0
	v_mul_f32_e32 v121, 0.5, v121
	v_add_f32_e32 v3, 1.0, v3
	v_mul_f32_e32 v121, v121, v3
	v_mul_f32_e32 v121, v121, v125
	v_mul_f32_e32 v121, v129, v121
	ds_write_b64 v222, v[120:121] offset:5120
	v_mul_f32_e32 v132, v138, v132
	v_mul_f32_e32 v0, 0x3f3504f3, v132
	v_mov_b32_e32 v6, s67
	v_fma_f32 v2, |v0|, s66, v6
	v_fma_f32 v2, |v0|, v2, s68
	v_fma_f32 v2, |v0|, v2, s69
	v_fma_f32 v2, |v0|, v2, s70
	v_fma_f32 v2, |v0|, v2, s71
	v_fma_f32 v2, |v0|, v2, s72
	v_fma_f32 v2, |v0|, v2, |v0|
	v_mul_f32_e32 v4, 0xbfb8aa3b, v2
	v_fma_f32 v5, v2, s73, -v4
	v_rndne_f32_e32 v6, v4
	v_fmac_f32_e32 v5, 0xb2a5705f, v2
	v_sub_f32_e32 v4, v4, v6
	v_add_f32_e32 v4, v4, v5
	v_cvt_i32_f32_e32 v5, v6
	v_exp_f32_e32 v4, v4
	v_cmp_nlt_f32_e64 s[82:83], s74, v2
	v_ldexp_f32 v4, v4, v5
	s_nop 0
	v_cndmask_b32_e64 v4, 0, v4, s[82:83]
	v_cmp_ngt_f32_e64 s[82:83], s75, v2
	v_mov_b32_e32 v6, 0x7f800000
	s_nop 0
	v_cndmask_b32_e64 v3, v6, v4, s[82:83]
	v_sub_f32_e32 v3, 1.0, v3
	v_mul_f32_e32 v4, v0, v0
	v_mov_b32_e32 v6, s76
	v_fmamk_f32 v5, v4, 0xba1345e1, v6
	v_fmaak_f32 v5, v4, v5, 0xbcdac9b8
	v_fmaak_f32 v5, v4, v5, 0x3de703be
	v_fmaak_f32 v5, v4, v5, 0xbec09330
	v_fmaak_f32 v4, v4, v5, 0x3e0375d0
	v_fma_f32 v7, |v0|, v4, |v0|
	v_cmp_nlt_f32_e64 s[82:83], |v0|, 1.0
	s_nop 1
	v_cndmask_b32_e64 v3, v7, v3, s[82:83]
	v_bfi_b32 v3, s77, v3, v0
	v_mul_f32_e32 v132, 0.5, v132
	v_add_f32_e32 v3, 1.0, v3
	v_mul_f32_e32 v132, v132, v3
	v_mul_f32_e32 v132, v132, v136
	v_mul_f32_e32 v132, v140, v132
	v_mul_f32_e32 v133, v139, v133
	v_mul_f32_e32 v0, 0x3f3504f3, v133
	v_mov_b32_e32 v6, s67
	v_fma_f32 v2, |v0|, s66, v6
	v_fma_f32 v2, |v0|, v2, s68
	v_fma_f32 v2, |v0|, v2, s69
	v_fma_f32 v2, |v0|, v2, s70
	v_fma_f32 v2, |v0|, v2, s71
	v_fma_f32 v2, |v0|, v2, s72
	v_fma_f32 v2, |v0|, v2, |v0|
	v_mul_f32_e32 v4, 0xbfb8aa3b, v2
	v_fma_f32 v5, v2, s73, -v4
	v_rndne_f32_e32 v6, v4
	v_fmac_f32_e32 v5, 0xb2a5705f, v2
	v_sub_f32_e32 v4, v4, v6
	v_add_f32_e32 v4, v4, v5
	v_cvt_i32_f32_e32 v5, v6
	v_exp_f32_e32 v4, v4
	v_cmp_nlt_f32_e64 s[82:83], s74, v2
	v_ldexp_f32 v4, v4, v5
	s_nop 0
	v_cndmask_b32_e64 v4, 0, v4, s[82:83]
	v_cmp_ngt_f32_e64 s[82:83], s75, v2
	v_mov_b32_e32 v6, 0x7f800000
	s_nop 0
	v_cndmask_b32_e64 v3, v6, v4, s[82:83]
	v_sub_f32_e32 v3, 1.0, v3
	v_mul_f32_e32 v4, v0, v0
	v_mov_b32_e32 v6, s76
	v_fmamk_f32 v5, v4, 0xba1345e1, v6
	v_fmaak_f32 v5, v4, v5, 0xbcdac9b8
	v_fmaak_f32 v5, v4, v5, 0x3de703be
	v_fmaak_f32 v5, v4, v5, 0xbec09330
	v_fmaak_f32 v4, v4, v5, 0x3e0375d0
	v_fma_f32 v7, |v0|, v4, |v0|
	v_cmp_nlt_f32_e64 s[82:83], |v0|, 1.0
	s_nop 1
	v_cndmask_b32_e64 v3, v7, v3, s[82:83]
	v_bfi_b32 v3, s77, v3, v0
	v_mul_f32_e32 v133, 0.5, v133
	v_add_f32_e32 v3, 1.0, v3
	v_mul_f32_e32 v133, v133, v3
	v_mul_f32_e32 v133, v133, v137
	v_mul_f32_e32 v133, v141, v133
	ds_write_b64 v222, v[132:133] offset:5632
	v_mul_f32_e32 v144, v150, v144
	v_mul_f32_e32 v0, 0x3f3504f3, v144
	v_mov_b32_e32 v6, s67
	v_fma_f32 v2, |v0|, s66, v6
	v_fma_f32 v2, |v0|, v2, s68
	v_fma_f32 v2, |v0|, v2, s69
	v_fma_f32 v2, |v0|, v2, s70
	v_fma_f32 v2, |v0|, v2, s71
	v_fma_f32 v2, |v0|, v2, s72
	v_fma_f32 v2, |v0|, v2, |v0|
	v_mul_f32_e32 v4, 0xbfb8aa3b, v2
	v_fma_f32 v5, v2, s73, -v4
	v_rndne_f32_e32 v6, v4
	v_fmac_f32_e32 v5, 0xb2a5705f, v2
	v_sub_f32_e32 v4, v4, v6
	v_add_f32_e32 v4, v4, v5
	v_cvt_i32_f32_e32 v5, v6
	v_exp_f32_e32 v4, v4
	v_cmp_nlt_f32_e64 s[82:83], s74, v2
	v_ldexp_f32 v4, v4, v5
	s_nop 0
	v_cndmask_b32_e64 v4, 0, v4, s[82:83]
	v_cmp_ngt_f32_e64 s[82:83], s75, v2
	v_mov_b32_e32 v6, 0x7f800000
	s_nop 0
	v_cndmask_b32_e64 v3, v6, v4, s[82:83]
	v_sub_f32_e32 v3, 1.0, v3
	v_mul_f32_e32 v4, v0, v0
	v_mov_b32_e32 v6, s76
	v_fmamk_f32 v5, v4, 0xba1345e1, v6
	v_fmaak_f32 v5, v4, v5, 0xbcdac9b8
	v_fmaak_f32 v5, v4, v5, 0x3de703be
	v_fmaak_f32 v5, v4, v5, 0xbec09330
	v_fmaak_f32 v4, v4, v5, 0x3e0375d0
	v_fma_f32 v7, |v0|, v4, |v0|
	v_cmp_nlt_f32_e64 s[82:83], |v0|, 1.0
	s_nop 1
	v_cndmask_b32_e64 v3, v7, v3, s[82:83]
	v_bfi_b32 v3, s77, v3, v0
	v_mul_f32_e32 v144, 0.5, v144
	v_add_f32_e32 v3, 1.0, v3
	v_mul_f32_e32 v144, v144, v3
	v_mul_f32_e32 v144, v144, v148
	v_mul_f32_e32 v144, v152, v144
	v_mul_f32_e32 v145, v151, v145
	v_mul_f32_e32 v0, 0x3f3504f3, v145
	v_mov_b32_e32 v6, s67
	v_fma_f32 v2, |v0|, s66, v6
	v_fma_f32 v2, |v0|, v2, s68
	v_fma_f32 v2, |v0|, v2, s69
	v_fma_f32 v2, |v0|, v2, s70
	v_fma_f32 v2, |v0|, v2, s71
	v_fma_f32 v2, |v0|, v2, s72
	v_fma_f32 v2, |v0|, v2, |v0|
	v_mul_f32_e32 v4, 0xbfb8aa3b, v2
	v_fma_f32 v5, v2, s73, -v4
	v_rndne_f32_e32 v6, v4
	v_fmac_f32_e32 v5, 0xb2a5705f, v2
	v_sub_f32_e32 v4, v4, v6
	v_add_f32_e32 v4, v4, v5
	v_cvt_i32_f32_e32 v5, v6
	v_exp_f32_e32 v4, v4
	v_cmp_nlt_f32_e64 s[82:83], s74, v2
	v_ldexp_f32 v4, v4, v5
	s_nop 0
	v_cndmask_b32_e64 v4, 0, v4, s[82:83]
	v_cmp_ngt_f32_e64 s[82:83], s75, v2
	v_mov_b32_e32 v6, 0x7f800000
	s_nop 0
	v_cndmask_b32_e64 v3, v6, v4, s[82:83]
	v_sub_f32_e32 v3, 1.0, v3
	v_mul_f32_e32 v4, v0, v0
	v_mov_b32_e32 v6, s76
	v_fmamk_f32 v5, v4, 0xba1345e1, v6
	v_fmaak_f32 v5, v4, v5, 0xbcdac9b8
	v_fmaak_f32 v5, v4, v5, 0x3de703be
	v_fmaak_f32 v5, v4, v5, 0xbec09330
	v_fmaak_f32 v4, v4, v5, 0x3e0375d0
	v_fma_f32 v7, |v0|, v4, |v0|
	v_cmp_nlt_f32_e64 s[82:83], |v0|, 1.0
	s_nop 1
	v_cndmask_b32_e64 v3, v7, v3, s[82:83]
	v_bfi_b32 v3, s77, v3, v0
	v_mul_f32_e32 v145, 0.5, v145
	v_add_f32_e32 v3, 1.0, v3
	v_mul_f32_e32 v145, v145, v3
	v_mul_f32_e32 v145, v145, v149
	v_mul_f32_e32 v145, v153, v145
	ds_write_b64 v222, v[144:145] offset:6144
	v_mul_f32_e32 v156, v162, v156
	v_mul_f32_e32 v0, 0x3f3504f3, v156
	v_mov_b32_e32 v6, s67
	v_fma_f32 v2, |v0|, s66, v6
	v_fma_f32 v2, |v0|, v2, s68
	v_fma_f32 v2, |v0|, v2, s69
	v_fma_f32 v2, |v0|, v2, s70
	v_fma_f32 v2, |v0|, v2, s71
	v_fma_f32 v2, |v0|, v2, s72
	v_fma_f32 v2, |v0|, v2, |v0|
	v_mul_f32_e32 v4, 0xbfb8aa3b, v2
	v_fma_f32 v5, v2, s73, -v4
	v_rndne_f32_e32 v6, v4
	v_fmac_f32_e32 v5, 0xb2a5705f, v2
	v_sub_f32_e32 v4, v4, v6
	v_add_f32_e32 v4, v4, v5
	v_cvt_i32_f32_e32 v5, v6
	v_exp_f32_e32 v4, v4
	v_cmp_nlt_f32_e64 s[82:83], s74, v2
	v_ldexp_f32 v4, v4, v5
	s_nop 0
	v_cndmask_b32_e64 v4, 0, v4, s[82:83]
	v_cmp_ngt_f32_e64 s[82:83], s75, v2
	v_mov_b32_e32 v6, 0x7f800000
	s_nop 0
	v_cndmask_b32_e64 v3, v6, v4, s[82:83]
	v_sub_f32_e32 v3, 1.0, v3
	v_mul_f32_e32 v4, v0, v0
	v_mov_b32_e32 v6, s76
	v_fmamk_f32 v5, v4, 0xba1345e1, v6
	v_fmaak_f32 v5, v4, v5, 0xbcdac9b8
	v_fmaak_f32 v5, v4, v5, 0x3de703be
	v_fmaak_f32 v5, v4, v5, 0xbec09330
	v_fmaak_f32 v4, v4, v5, 0x3e0375d0
	v_fma_f32 v7, |v0|, v4, |v0|
	v_cmp_nlt_f32_e64 s[82:83], |v0|, 1.0
	s_nop 1
	v_cndmask_b32_e64 v3, v7, v3, s[82:83]
	v_bfi_b32 v3, s77, v3, v0
	v_mul_f32_e32 v156, 0.5, v156
	v_add_f32_e32 v3, 1.0, v3
	v_mul_f32_e32 v156, v156, v3
	v_mul_f32_e32 v156, v156, v160
	v_mul_f32_e32 v156, v164, v156
	v_mul_f32_e32 v157, v163, v157
	v_mul_f32_e32 v0, 0x3f3504f3, v157
	v_mov_b32_e32 v6, s67
	v_fma_f32 v2, |v0|, s66, v6
	v_fma_f32 v2, |v0|, v2, s68
	v_fma_f32 v2, |v0|, v2, s69
	v_fma_f32 v2, |v0|, v2, s70
	v_fma_f32 v2, |v0|, v2, s71
	v_fma_f32 v2, |v0|, v2, s72
	v_fma_f32 v2, |v0|, v2, |v0|
	v_mul_f32_e32 v4, 0xbfb8aa3b, v2
	v_fma_f32 v5, v2, s73, -v4
	v_rndne_f32_e32 v6, v4
	v_fmac_f32_e32 v5, 0xb2a5705f, v2
	v_sub_f32_e32 v4, v4, v6
	v_add_f32_e32 v4, v4, v5
	v_cvt_i32_f32_e32 v5, v6
	v_exp_f32_e32 v4, v4
	v_cmp_nlt_f32_e64 s[82:83], s74, v2
	v_ldexp_f32 v4, v4, v5
	s_nop 0
	v_cndmask_b32_e64 v4, 0, v4, s[82:83]
	v_cmp_ngt_f32_e64 s[82:83], s75, v2
	v_mov_b32_e32 v6, 0x7f800000
	s_nop 0
	v_cndmask_b32_e64 v3, v6, v4, s[82:83]
	v_sub_f32_e32 v3, 1.0, v3
	v_mul_f32_e32 v4, v0, v0
	v_mov_b32_e32 v6, s76
	v_fmamk_f32 v5, v4, 0xba1345e1, v6
	v_fmaak_f32 v5, v4, v5, 0xbcdac9b8
	v_fmaak_f32 v5, v4, v5, 0x3de703be
	v_fmaak_f32 v5, v4, v5, 0xbec09330
	v_fmaak_f32 v4, v4, v5, 0x3e0375d0
	v_fma_f32 v7, |v0|, v4, |v0|
	v_cmp_nlt_f32_e64 s[82:83], |v0|, 1.0
	s_nop 1
	v_cndmask_b32_e64 v3, v7, v3, s[82:83]
	v_bfi_b32 v3, s77, v3, v0
	v_mul_f32_e32 v157, 0.5, v157
	v_add_f32_e32 v3, 1.0, v3
	v_mul_f32_e32 v157, v157, v3
	v_mul_f32_e32 v157, v157, v161
	v_mul_f32_e32 v157, v165, v157
	ds_write_b64 v222, v[156:157] offset:6656
	v_mul_f32_e32 v168, v174, v168
	v_mul_f32_e32 v0, 0x3f3504f3, v168
	v_mov_b32_e32 v6, s67
	v_fma_f32 v2, |v0|, s66, v6
	v_fma_f32 v2, |v0|, v2, s68
	v_fma_f32 v2, |v0|, v2, s69
	v_fma_f32 v2, |v0|, v2, s70
	v_fma_f32 v2, |v0|, v2, s71
	v_fma_f32 v2, |v0|, v2, s72
	v_fma_f32 v2, |v0|, v2, |v0|
	v_mul_f32_e32 v4, 0xbfb8aa3b, v2
	v_fma_f32 v5, v2, s73, -v4
	v_rndne_f32_e32 v6, v4
	v_fmac_f32_e32 v5, 0xb2a5705f, v2
	v_sub_f32_e32 v4, v4, v6
	v_add_f32_e32 v4, v4, v5
	v_cvt_i32_f32_e32 v5, v6
	v_exp_f32_e32 v4, v4
	v_cmp_nlt_f32_e64 s[82:83], s74, v2
	v_ldexp_f32 v4, v4, v5
	s_nop 0
	v_cndmask_b32_e64 v4, 0, v4, s[82:83]
	v_cmp_ngt_f32_e64 s[82:83], s75, v2
	v_mov_b32_e32 v6, 0x7f800000
	s_nop 0
	v_cndmask_b32_e64 v3, v6, v4, s[82:83]
	v_sub_f32_e32 v3, 1.0, v3
	v_mul_f32_e32 v4, v0, v0
	v_mov_b32_e32 v6, s76
	v_fmamk_f32 v5, v4, 0xba1345e1, v6
	v_fmaak_f32 v5, v4, v5, 0xbcdac9b8
	v_fmaak_f32 v5, v4, v5, 0x3de703be
	v_fmaak_f32 v5, v4, v5, 0xbec09330
	v_fmaak_f32 v4, v4, v5, 0x3e0375d0
	v_fma_f32 v7, |v0|, v4, |v0|
	v_cmp_nlt_f32_e64 s[82:83], |v0|, 1.0
	s_nop 1
	v_cndmask_b32_e64 v3, v7, v3, s[82:83]
	v_bfi_b32 v3, s77, v3, v0
	v_mul_f32_e32 v168, 0.5, v168
	v_add_f32_e32 v3, 1.0, v3
	v_mul_f32_e32 v168, v168, v3
	v_mul_f32_e32 v168, v168, v172
	v_mul_f32_e32 v168, v176, v168
	v_mul_f32_e32 v169, v175, v169
	v_mul_f32_e32 v0, 0x3f3504f3, v169
	v_mov_b32_e32 v6, s67
	v_fma_f32 v2, |v0|, s66, v6
	v_fma_f32 v2, |v0|, v2, s68
	v_fma_f32 v2, |v0|, v2, s69
	v_fma_f32 v2, |v0|, v2, s70
	v_fma_f32 v2, |v0|, v2, s71
	v_fma_f32 v2, |v0|, v2, s72
	v_fma_f32 v2, |v0|, v2, |v0|
	v_mul_f32_e32 v4, 0xbfb8aa3b, v2
	v_fma_f32 v5, v2, s73, -v4
	v_rndne_f32_e32 v6, v4
	v_fmac_f32_e32 v5, 0xb2a5705f, v2
	v_sub_f32_e32 v4, v4, v6
	v_add_f32_e32 v4, v4, v5
	v_cvt_i32_f32_e32 v5, v6
	v_exp_f32_e32 v4, v4
	v_cmp_nlt_f32_e64 s[82:83], s74, v2
	v_ldexp_f32 v4, v4, v5
	s_nop 0
	v_cndmask_b32_e64 v4, 0, v4, s[82:83]
	v_cmp_ngt_f32_e64 s[82:83], s75, v2
	v_mov_b32_e32 v6, 0x7f800000
	s_nop 0
	v_cndmask_b32_e64 v3, v6, v4, s[82:83]
	v_sub_f32_e32 v3, 1.0, v3
	v_mul_f32_e32 v4, v0, v0
	v_mov_b32_e32 v6, s76
	v_fmamk_f32 v5, v4, 0xba1345e1, v6
	v_fmaak_f32 v5, v4, v5, 0xbcdac9b8
	v_fmaak_f32 v5, v4, v5, 0x3de703be
	v_fmaak_f32 v5, v4, v5, 0xbec09330
	v_fmaak_f32 v4, v4, v5, 0x3e0375d0
	v_fma_f32 v7, |v0|, v4, |v0|
	v_cmp_nlt_f32_e64 s[82:83], |v0|, 1.0
	s_nop 1
	v_cndmask_b32_e64 v3, v7, v3, s[82:83]
	v_bfi_b32 v3, s77, v3, v0
	v_mul_f32_e32 v169, 0.5, v169
	v_add_f32_e32 v3, 1.0, v3
	v_mul_f32_e32 v169, v169, v3
	v_mul_f32_e32 v169, v169, v173
	v_mul_f32_e32 v169, v177, v169
	ds_write_b64 v222, v[168:169] offset:7168
	v_mul_f32_e32 v180, v186, v180
	v_mul_f32_e32 v0, 0x3f3504f3, v180
	v_mov_b32_e32 v6, s67
	v_fma_f32 v2, |v0|, s66, v6
	v_fma_f32 v2, |v0|, v2, s68
	v_fma_f32 v2, |v0|, v2, s69
	v_fma_f32 v2, |v0|, v2, s70
	v_fma_f32 v2, |v0|, v2, s71
	v_fma_f32 v2, |v0|, v2, s72
	v_fma_f32 v2, |v0|, v2, |v0|
	v_mul_f32_e32 v4, 0xbfb8aa3b, v2
	v_fma_f32 v5, v2, s73, -v4
	v_rndne_f32_e32 v6, v4
	v_fmac_f32_e32 v5, 0xb2a5705f, v2
	v_sub_f32_e32 v4, v4, v6
	v_add_f32_e32 v4, v4, v5
	v_cvt_i32_f32_e32 v5, v6
	v_exp_f32_e32 v4, v4
	v_cmp_nlt_f32_e64 s[82:83], s74, v2
	v_ldexp_f32 v4, v4, v5
	s_nop 0
	v_cndmask_b32_e64 v4, 0, v4, s[82:83]
	v_cmp_ngt_f32_e64 s[82:83], s75, v2
	v_mov_b32_e32 v6, 0x7f800000
	s_nop 0
	v_cndmask_b32_e64 v3, v6, v4, s[82:83]
	v_sub_f32_e32 v3, 1.0, v3
	v_mul_f32_e32 v4, v0, v0
	v_mov_b32_e32 v6, s76
	v_fmamk_f32 v5, v4, 0xba1345e1, v6
	v_fmaak_f32 v5, v4, v5, 0xbcdac9b8
	v_fmaak_f32 v5, v4, v5, 0x3de703be
	v_fmaak_f32 v5, v4, v5, 0xbec09330
	v_fmaak_f32 v4, v4, v5, 0x3e0375d0
	v_fma_f32 v7, |v0|, v4, |v0|
	v_cmp_nlt_f32_e64 s[82:83], |v0|, 1.0
	s_nop 1
	v_cndmask_b32_e64 v3, v7, v3, s[82:83]
	v_bfi_b32 v3, s77, v3, v0
	v_mul_f32_e32 v180, 0.5, v180
	v_add_f32_e32 v3, 1.0, v3
	v_mul_f32_e32 v180, v180, v3
	v_mul_f32_e32 v180, v180, v184
	v_mul_f32_e32 v180, v188, v180
	v_mul_f32_e32 v181, v187, v181
	v_mul_f32_e32 v0, 0x3f3504f3, v181
	v_mov_b32_e32 v6, s67
	v_fma_f32 v2, |v0|, s66, v6
	v_fma_f32 v2, |v0|, v2, s68
	v_fma_f32 v2, |v0|, v2, s69
	v_fma_f32 v2, |v0|, v2, s70
	v_fma_f32 v2, |v0|, v2, s71
	v_fma_f32 v2, |v0|, v2, s72
	v_fma_f32 v2, |v0|, v2, |v0|
	v_mul_f32_e32 v4, 0xbfb8aa3b, v2
	v_fma_f32 v5, v2, s73, -v4
	v_rndne_f32_e32 v6, v4
	v_fmac_f32_e32 v5, 0xb2a5705f, v2
	v_sub_f32_e32 v4, v4, v6
	v_add_f32_e32 v4, v4, v5
	v_cvt_i32_f32_e32 v5, v6
	v_exp_f32_e32 v4, v4
	v_cmp_nlt_f32_e64 s[82:83], s74, v2
	v_ldexp_f32 v4, v4, v5
	s_nop 0
	v_cndmask_b32_e64 v4, 0, v4, s[82:83]
	v_cmp_ngt_f32_e64 s[82:83], s75, v2
	v_mov_b32_e32 v6, 0x7f800000
	s_nop 0
	v_cndmask_b32_e64 v3, v6, v4, s[82:83]
	v_sub_f32_e32 v3, 1.0, v3
	v_mul_f32_e32 v4, v0, v0
	v_mov_b32_e32 v6, s76
	v_fmamk_f32 v5, v4, 0xba1345e1, v6
	v_fmaak_f32 v5, v4, v5, 0xbcdac9b8
	v_fmaak_f32 v5, v4, v5, 0x3de703be
	v_fmaak_f32 v5, v4, v5, 0xbec09330
	v_fmaak_f32 v4, v4, v5, 0x3e0375d0
	v_fma_f32 v7, |v0|, v4, |v0|
	v_cmp_nlt_f32_e64 s[82:83], |v0|, 1.0
	s_nop 1
	v_cndmask_b32_e64 v3, v7, v3, s[82:83]
	v_bfi_b32 v3, s77, v3, v0
	v_mul_f32_e32 v181, 0.5, v181
	v_add_f32_e32 v3, 1.0, v3
	v_mul_f32_e32 v181, v181, v3
	v_mul_f32_e32 v181, v181, v185
	v_mul_f32_e32 v181, v189, v181
	ds_write_b64 v222, v[180:181] offset:7680
	s_waitcnt lgkmcnt(0)
	s_mov_b32 s8, 8
	s_mov_b32 s7, 0
	s_mov_b32 s54, 8
	s_mov_b32 s53, 0
	s_mul_i32 s55, s53, s5
	s_add_i32 s55, s55, s6
	s_min_u32 s55, s55, 0x3fff
	s_and_b32 s34, s54, 7
	s_mul_i32 s34, s34, 0x300000
	s_cmp_lt_u32 s54, 8
	s_cselect_b32 s30, s16, s18
	s_cselect_b32 s31, s17, s19
	s_add_u32 s30, s30, s34
	s_addc_u32 s31, s31, 0
	s_and_b32 s34, s54, 7
	s_lshl_b32 s34, s34, 6
	s_lshl_b32 s35, s55, 12
	s_add_u32 s34, s34, s35
	s_add_u32 s32, s24, s34
	s_addc_u32 s33, s25, 0
	s_and_b32 s34, s54, 7
	s_lshl_b32 s34, s34, 7
	s_lshr_b32 s35, s55, 13
	s_mul_i32 s35, s35, 0xc000
	s_add_u32 s35, s35, s34
	s_add_u32 s35, s35, 0xa000
	s_add_u32 s58, s26, s35
	s_addc_u32 s59, s27, 0
	s_lshl_b32 s35, s55, 13
	s_add_u32 s35, s35, s34
	s_add_u32 s60, s28, s35
	s_addc_u32 s61, s29, 0
	s_mul_i32 s34, s53, s5
	s_add_i32 s34, s34, s6
	s_cmp_lt_u32 s34, 0x4000
	s_cselect_b32 s57, 1, 0
	s_lshl_b32 s34, s53, 9
	v_add_u32_e32 v216, s34, v223
	ds_read_b128 v[80:83], v216 offset:0
	ds_read_b128 v[84:87], v216 offset:16
	ds_read_b128 v[88:91], v216 offset:32
	ds_read_b128 v[92:95], v216 offset:48
	s_waitcnt lgkmcnt(0)
	global_load_dwordx2 v[64:65], v225, s[32:33]
	global_load_dwordx4 v[66:69], v226, s[58:59]
	v_mad_u32_u24 v217, v80, s52, v220
	v_add_u32_e32 v218, v217, v221
	global_load_dwordx4 v[96:99], v217, s[30:31]
	global_load_dwordx2 v[100:101], v218, s[30:31]
	v_mad_u32_u24 v217, v81, s52, v220
	v_add_u32_e32 v218, v217, v221
	global_load_dwordx4 v[102:105], v217, s[30:31]
	global_load_dwordx2 v[106:107], v218, s[30:31]
	v_mad_u32_u24 v217, v82, s52, v220
	v_add_u32_e32 v218, v217, v221
	global_load_dwordx4 v[108:111], v217, s[30:31]
	global_load_dwordx2 v[112:113], v218, s[30:31]
	v_mad_u32_u24 v217, v83, s52, v220
	v_add_u32_e32 v218, v217, v221
	global_load_dwordx4 v[114:117], v217, s[30:31]
	global_load_dwordx2 v[118:119], v218, s[30:31]
	v_mad_u32_u24 v217, v84, s52, v220
	v_add_u32_e32 v218, v217, v221
	global_load_dwordx4 v[120:123], v217, s[30:31]
	global_load_dwordx2 v[124:125], v218, s[30:31]
	v_mad_u32_u24 v217, v85, s52, v220
	v_add_u32_e32 v218, v217, v221
	global_load_dwordx4 v[126:129], v217, s[30:31]
	global_load_dwordx2 v[130:131], v218, s[30:31]
	v_mad_u32_u24 v217, v86, s52, v220
	v_add_u32_e32 v218, v217, v221
	global_load_dwordx4 v[132:135], v217, s[30:31]
	global_load_dwordx2 v[136:137], v218, s[30:31]
	v_mad_u32_u24 v217, v87, s52, v220
	v_add_u32_e32 v218, v217, v221
	global_load_dwordx4 v[138:141], v217, s[30:31]
	global_load_dwordx2 v[142:143], v218, s[30:31]
	v_mad_u32_u24 v217, v88, s52, v220
	v_add_u32_e32 v218, v217, v221
	global_load_dwordx4 v[144:147], v217, s[30:31]
	global_load_dwordx2 v[148:149], v218, s[30:31]
	v_mad_u32_u24 v217, v89, s52, v220
	v_add_u32_e32 v218, v217, v221
	global_load_dwordx4 v[150:153], v217, s[30:31]
	global_load_dwordx2 v[154:155], v218, s[30:31]
	v_mad_u32_u24 v217, v90, s52, v220
	v_add_u32_e32 v218, v217, v221
	global_load_dwordx4 v[156:159], v217, s[30:31]
	global_load_dwordx2 v[160:161], v218, s[30:31]
	v_mad_u32_u24 v217, v91, s52, v220
	v_add_u32_e32 v218, v217, v221
	global_load_dwordx4 v[162:165], v217, s[30:31]
	global_load_dwordx2 v[166:167], v218, s[30:31]
	v_mad_u32_u24 v217, v92, s52, v220
	v_add_u32_e32 v218, v217, v221
	global_load_dwordx4 v[168:171], v217, s[30:31]
	global_load_dwordx2 v[172:173], v218, s[30:31]
	v_mad_u32_u24 v217, v93, s52, v220
	v_add_u32_e32 v218, v217, v221
	global_load_dwordx4 v[174:177], v217, s[30:31]
	global_load_dwordx2 v[178:179], v218, s[30:31]
	v_mad_u32_u24 v217, v94, s52, v220
	v_add_u32_e32 v218, v217, v221
	global_load_dwordx4 v[180:183], v217, s[30:31]
	global_load_dwordx2 v[184:185], v218, s[30:31]
	v_mad_u32_u24 v217, v95, s52, v220
	v_add_u32_e32 v218, v217, v221
	global_load_dwordx4 v[186:189], v217, s[30:31]
	global_load_dwordx2 v[190:191], v218, s[30:31]
	global_load_dword v219, v231, s[28:29]
.Lex_vloop:
	s_mov_b32 s78, s60
	s_mov_b32 s79, s61
	s_mov_b32 s80, s57
	s_lshl_b32 s34, s7, 9
	v_add_u32_e32 v216, s34, v229
	ds_read_b128 v[192:195], v216 offset:0
	ds_read_b128 v[196:199], v216 offset:16
	ds_read_b128 v[200:203], v216 offset:32
	ds_read_b128 v[204:207], v216 offset:48
	s_waitcnt vmcnt(33)
	v_mov_b32_e32 v72, v64
	v_mov_b32_e32 v73, v65
	v_mov_b32_e32 v74, v66
	v_mov_b32_e32 v75, v67
	v_mov_b32_e32 v76, v68
	v_mov_b32_e32 v77, v69
	s_add_i32 s53, s7, 1
	s_mov_b32 s54, s8
	s_cmp_eq_u32 s53, 8
	s_cselect_b32 s53, 0, s53
	s_cselect_b32 s34, 1, 0
	s_add_i32 s54, s54, s34
	s_mul_i32 s55, s53, s5
	s_add_i32 s55, s55, s6
	s_min_u32 s55, s55, 0x3fff
	s_and_b32 s34, s54, 7
	s_mul_i32 s34, s34, 0x300000
	s_cmp_lt_u32 s54, 8
	s_cselect_b32 s30, s16, s18
	s_cselect_b32 s31, s17, s19
	s_add_u32 s30, s30, s34
	s_addc_u32 s31, s31, 0
	s_and_b32 s34, s54, 7
	s_lshl_b32 s34, s34, 6
	s_lshl_b32 s35, s55, 12
	s_add_u32 s34, s34, s35
	s_add_u32 s32, s24, s34
	s_addc_u32 s33, s25, 0
	s_and_b32 s34, s54, 7
	s_lshl_b32 s34, s34, 7
	s_lshr_b32 s35, s55, 13
	s_mul_i32 s35, s35, 0xc000
	s_add_u32 s35, s35, s34
	s_add_u32 s35, s35, 0xa000
	s_add_u32 s58, s26, s35
	s_addc_u32 s59, s27, 0
	s_lshl_b32 s35, s55, 13
	s_add_u32 s35, s35, s34
	s_add_u32 s60, s28, s35
	s_addc_u32 s61, s29, 0
	s_mul_i32 s34, s53, s5
	s_add_i32 s34, s34, s6
	s_cmp_lt_u32 s34, 0x4000
	s_cselect_b32 s57, 1, 0
	s_lshl_b32 s34, s53, 9
	v_add_u32_e32 v216, s34, v223
	ds_read_b128 v[80:83], v216 offset:0
	ds_read_b128 v[84:87], v216 offset:16
	ds_read_b128 v[88:91], v216 offset:32
	ds_read_b128 v[92:95], v216 offset:48
	s_waitcnt lgkmcnt(4)
	s_waitcnt vmcnt(31)
	v_cvt_scalef32_pk32_f32_fp6 v[0:31], v[96:101], 1.0
	v_pk_mul_f32 v[32:33], v[192:193], v[0:1] op_sel_hi:[0,1]
	v_pk_mul_f32 v[34:35], v[192:193], v[2:3] op_sel_hi:[0,1]
	v_pk_mul_f32 v[36:37], v[192:193], v[4:5] op_sel_hi:[0,1]
	v_pk_mul_f32 v[38:39], v[192:193], v[6:7] op_sel_hi:[0,1]
	v_pk_mul_f32 v[40:41], v[192:193], v[8:9] op_sel_hi:[0,1]
	v_pk_mul_f32 v[42:43], v[192:193], v[10:11] op_sel_hi:[0,1]
	v_pk_mul_f32 v[44:45], v[192:193], v[12:13] op_sel_hi:[0,1]
	v_pk_mul_f32 v[46:47], v[192:193], v[14:15] op_sel_hi:[0,1]
	v_pk_mul_f32 v[48:49], v[192:193], v[16:17] op_sel_hi:[0,1]
	v_pk_mul_f32 v[50:51], v[192:193], v[18:19] op_sel_hi:[0,1]
	v_pk_mul_f32 v[52:53], v[192:193], v[20:21] op_sel_hi:[0,1]
	v_pk_mul_f32 v[54:55], v[192:193], v[22:23] op_sel_hi:[0,1]
	v_pk_mul_f32 v[56:57], v[192:193], v[24:25] op_sel_hi:[0,1]
	v_pk_mul_f32 v[58:59], v[192:193], v[26:27] op_sel_hi:[0,1]
	v_pk_mul_f32 v[60:61], v[192:193], v[28:29] op_sel_hi:[0,1]
	v_pk_mul_f32 v[62:63], v[192:193], v[30:31] op_sel_hi:[0,1]
	s_waitcnt vmcnt(29)
	v_cvt_scalef32_pk32_f32_fp6 v[0:31], v[102:107], 1.0
	v_pk_fma_f32 v[32:33], v[192:193], v[0:1], v[32:33] op_sel:[1,0,0] op_sel_hi:[1,1,1]
	v_pk_fma_f32 v[34:35], v[192:193], v[2:3], v[34:35] op_sel:[1,0,0] op_sel_hi:[1,1,1]
	v_pk_fma_f32 v[36:37], v[192:193], v[4:5], v[36:37] op_sel:[1,0,0] op_sel_hi:[1,1,1]
	v_pk_fma_f32 v[38:39], v[192:193], v[6:7], v[38:39] op_sel:[1,0,0] op_sel_hi:[1,1,1]
	v_pk_fma_f32 v[40:41], v[192:193], v[8:9], v[40:41] op_sel:[1,0,0] op_sel_hi:[1,1,1]
	v_pk_fma_f32 v[42:43], v[192:193], v[10:11], v[42:43] op_sel:[1,0,0] op_sel_hi:[1,1,1]
	v_pk_fma_f32 v[44:45], v[192:193], v[12:13], v[44:45] op_sel:[1,0,0] op_sel_hi:[1,1,1]
	v_pk_fma_f32 v[46:47], v[192:193], v[14:15], v[46:47] op_sel:[1,0,0] op_sel_hi:[1,1,1]
	v_pk_fma_f32 v[48:49], v[192:193], v[16:17], v[48:49] op_sel:[1,0,0] op_sel_hi:[1,1,1]
	v_pk_fma_f32 v[50:51], v[192:193], v[18:19], v[50:51] op_sel:[1,0,0] op_sel_hi:[1,1,1]
	v_pk_fma_f32 v[52:53], v[192:193], v[20:21], v[52:53] op_sel:[1,0,0] op_sel_hi:[1,1,1]
	v_pk_fma_f32 v[54:55], v[192:193], v[22:23], v[54:55] op_sel:[1,0,0] op_sel_hi:[1,1,1]
	v_pk_fma_f32 v[56:57], v[192:193], v[24:25], v[56:57] op_sel:[1,0,0] op_sel_hi:[1,1,1]
	v_pk_fma_f32 v[58:59], v[192:193], v[26:27], v[58:59] op_sel:[1,0,0] op_sel_hi:[1,1,1]
	v_pk_fma_f32 v[60:61], v[192:193], v[28:29], v[60:61] op_sel:[1,0,0] op_sel_hi:[1,1,1]
	v_pk_fma_f32 v[62:63], v[192:193], v[30:31], v[62:63] op_sel:[1,0,0] op_sel_hi:[1,1,1]
	s_waitcnt vmcnt(27)
	v_cvt_scalef32_pk32_f32_fp6 v[0:31], v[108:113], 1.0
	v_pk_fma_f32 v[32:33], v[194:195], v[0:1], v[32:33] op_sel_hi:[0,1,1]
	v_pk_fma_f32 v[34:35], v[194:195], v[2:3], v[34:35] op_sel_hi:[0,1,1]
	v_pk_fma_f32 v[36:37], v[194:195], v[4:5], v[36:37] op_sel_hi:[0,1,1]
	v_pk_fma_f32 v[38:39], v[194:195], v[6:7], v[38:39] op_sel_hi:[0,1,1]
	v_pk_fma_f32 v[40:41], v[194:195], v[8:9], v[40:41] op_sel_hi:[0,1,1]
	v_pk_fma_f32 v[42:43], v[194:195], v[10:11], v[42:43] op_sel_hi:[0,1,1]
	v_pk_fma_f32 v[44:45], v[194:195], v[12:13], v[44:45] op_sel_hi:[0,1,1]
	v_pk_fma_f32 v[46:47], v[194:195], v[14:15], v[46:47] op_sel_hi:[0,1,1]
	v_pk_fma_f32 v[48:49], v[194:195], v[16:17], v[48:49] op_sel_hi:[0,1,1]
	v_pk_fma_f32 v[50:51], v[194:195], v[18:19], v[50:51] op_sel_hi:[0,1,1]
	v_pk_fma_f32 v[52:53], v[194:195], v[20:21], v[52:53] op_sel_hi:[0,1,1]
	v_pk_fma_f32 v[54:55], v[194:195], v[22:23], v[54:55] op_sel_hi:[0,1,1]
	v_pk_fma_f32 v[56:57], v[194:195], v[24:25], v[56:57] op_sel_hi:[0,1,1]
	v_pk_fma_f32 v[58:59], v[194:195], v[26:27], v[58:59] op_sel_hi:[0,1,1]
	v_pk_fma_f32 v[60:61], v[194:195], v[28:29], v[60:61] op_sel_hi:[0,1,1]
	v_pk_fma_f32 v[62:63], v[194:195], v[30:31], v[62:63] op_sel_hi:[0,1,1]
	s_waitcnt vmcnt(25)
	v_cvt_scalef32_pk32_f32_fp6 v[0:31], v[114:119], 1.0
	v_pk_fma_f32 v[32:33], v[194:195], v[0:1], v[32:33] op_sel:[1,0,0] op_sel_hi:[1,1,1]
	v_pk_fma_f32 v[34:35], v[194:195], v[2:3], v[34:35] op_sel:[1,0,0] op_sel_hi:[1,1,1]
	v_pk_fma_f32 v[36:37], v[194:195], v[4:5], v[36:37] op_sel:[1,0,0] op_sel_hi:[1,1,1]
	v_pk_fma_f32 v[38:39], v[194:195], v[6:7], v[38:39] op_sel:[1,0,0] op_sel_hi:[1,1,1]
	v_pk_fma_f32 v[40:41], v[194:195], v[8:9], v[40:41] op_sel:[1,0,0] op_sel_hi:[1,1,1]
	v_pk_fma_f32 v[42:43], v[194:195], v[10:11], v[42:43] op_sel:[1,0,0] op_sel_hi:[1,1,1]
	v_pk_fma_f32 v[44:45], v[194:195], v[12:13], v[44:45] op_sel:[1,0,0] op_sel_hi:[1,1,1]
	v_pk_fma_f32 v[46:47], v[194:195], v[14:15], v[46:47] op_sel:[1,0,0] op_sel_hi:[1,1,1]
	v_pk_fma_f32 v[48:49], v[194:195], v[16:17], v[48:49] op_sel:[1,0,0] op_sel_hi:[1,1,1]
	v_pk_fma_f32 v[50:51], v[194:195], v[18:19], v[50:51] op_sel:[1,0,0] op_sel_hi:[1,1,1]
	v_pk_fma_f32 v[52:53], v[194:195], v[20:21], v[52:53] op_sel:[1,0,0] op_sel_hi:[1,1,1]
	v_pk_fma_f32 v[54:55], v[194:195], v[22:23], v[54:55] op_sel:[1,0,0] op_sel_hi:[1,1,1]
	v_pk_fma_f32 v[56:57], v[194:195], v[24:25], v[56:57] op_sel:[1,0,0] op_sel_hi:[1,1,1]
	v_pk_fma_f32 v[58:59], v[194:195], v[26:27], v[58:59] op_sel:[1,0,0] op_sel_hi:[1,1,1]
	v_pk_fma_f32 v[60:61], v[194:195], v[28:29], v[60:61] op_sel:[1,0,0] op_sel_hi:[1,1,1]
	v_pk_fma_f32 v[62:63], v[194:195], v[30:31], v[62:63] op_sel:[1,0,0] op_sel_hi:[1,1,1]
	s_waitcnt vmcnt(23)
	v_cvt_scalef32_pk32_f32_fp6 v[0:31], v[120:125], 1.0
	v_pk_fma_f32 v[32:33], v[196:197], v[0:1], v[32:33] op_sel_hi:[0,1,1]
	v_pk_fma_f32 v[34:35], v[196:197], v[2:3], v[34:35] op_sel_hi:[0,1,1]
	v_pk_fma_f32 v[36:37], v[196:197], v[4:5], v[36:37] op_sel_hi:[0,1,1]
	v_pk_fma_f32 v[38:39], v[196:197], v[6:7], v[38:39] op_sel_hi:[0,1,1]
	v_pk_fma_f32 v[40:41], v[196:197], v[8:9], v[40:41] op_sel_hi:[0,1,1]
	v_pk_fma_f32 v[42:43], v[196:197], v[10:11], v[42:43] op_sel_hi:[0,1,1]
	v_pk_fma_f32 v[44:45], v[196:197], v[12:13], v[44:45] op_sel_hi:[0,1,1]
	v_pk_fma_f32 v[46:47], v[196:197], v[14:15], v[46:47] op_sel_hi:[0,1,1]
	v_pk_fma_f32 v[48:49], v[196:197], v[16:17], v[48:49] op_sel_hi:[0,1,1]
	v_pk_fma_f32 v[50:51], v[196:197], v[18:19], v[50:51] op_sel_hi:[0,1,1]
	v_pk_fma_f32 v[52:53], v[196:197], v[20:21], v[52:53] op_sel_hi:[0,1,1]
	v_pk_fma_f32 v[54:55], v[196:197], v[22:23], v[54:55] op_sel_hi:[0,1,1]
	v_pk_fma_f32 v[56:57], v[196:197], v[24:25], v[56:57] op_sel_hi:[0,1,1]
	v_pk_fma_f32 v[58:59], v[196:197], v[26:27], v[58:59] op_sel_hi:[0,1,1]
	v_pk_fma_f32 v[60:61], v[196:197], v[28:29], v[60:61] op_sel_hi:[0,1,1]
	v_pk_fma_f32 v[62:63], v[196:197], v[30:31], v[62:63] op_sel_hi:[0,1,1]
	s_waitcnt vmcnt(21)
	v_cvt_scalef32_pk32_f32_fp6 v[0:31], v[126:131], 1.0
	v_pk_fma_f32 v[32:33], v[196:197], v[0:1], v[32:33] op_sel:[1,0,0] op_sel_hi:[1,1,1]
	v_pk_fma_f32 v[34:35], v[196:197], v[2:3], v[34:35] op_sel:[1,0,0] op_sel_hi:[1,1,1]
	v_pk_fma_f32 v[36:37], v[196:197], v[4:5], v[36:37] op_sel:[1,0,0] op_sel_hi:[1,1,1]
	v_pk_fma_f32 v[38:39], v[196:197], v[6:7], v[38:39] op_sel:[1,0,0] op_sel_hi:[1,1,1]
	v_pk_fma_f32 v[40:41], v[196:197], v[8:9], v[40:41] op_sel:[1,0,0] op_sel_hi:[1,1,1]
	v_pk_fma_f32 v[42:43], v[196:197], v[10:11], v[42:43] op_sel:[1,0,0] op_sel_hi:[1,1,1]
	v_pk_fma_f32 v[44:45], v[196:197], v[12:13], v[44:45] op_sel:[1,0,0] op_sel_hi:[1,1,1]
	v_pk_fma_f32 v[46:47], v[196:197], v[14:15], v[46:47] op_sel:[1,0,0] op_sel_hi:[1,1,1]
	v_pk_fma_f32 v[48:49], v[196:197], v[16:17], v[48:49] op_sel:[1,0,0] op_sel_hi:[1,1,1]
	v_pk_fma_f32 v[50:51], v[196:197], v[18:19], v[50:51] op_sel:[1,0,0] op_sel_hi:[1,1,1]
	v_pk_fma_f32 v[52:53], v[196:197], v[20:21], v[52:53] op_sel:[1,0,0] op_sel_hi:[1,1,1]
	v_pk_fma_f32 v[54:55], v[196:197], v[22:23], v[54:55] op_sel:[1,0,0] op_sel_hi:[1,1,1]
	v_pk_fma_f32 v[56:57], v[196:197], v[24:25], v[56:57] op_sel:[1,0,0] op_sel_hi:[1,1,1]
	v_pk_fma_f32 v[58:59], v[196:197], v[26:27], v[58:59] op_sel:[1,0,0] op_sel_hi:[1,1,1]
	v_pk_fma_f32 v[60:61], v[196:197], v[28:29], v[60:61] op_sel:[1,0,0] op_sel_hi:[1,1,1]
	v_pk_fma_f32 v[62:63], v[196:197], v[30:31], v[62:63] op_sel:[1,0,0] op_sel_hi:[1,1,1]
	s_waitcnt vmcnt(19)
	v_cvt_scalef32_pk32_f32_fp6 v[0:31], v[132:137], 1.0
	v_pk_fma_f32 v[32:33], v[198:199], v[0:1], v[32:33] op_sel_hi:[0,1,1]
	v_pk_fma_f32 v[34:35], v[198:199], v[2:3], v[34:35] op_sel_hi:[0,1,1]
	v_pk_fma_f32 v[36:37], v[198:199], v[4:5], v[36:37] op_sel_hi:[0,1,1]
	v_pk_fma_f32 v[38:39], v[198:199], v[6:7], v[38:39] op_sel_hi:[0,1,1]
	v_pk_fma_f32 v[40:41], v[198:199], v[8:9], v[40:41] op_sel_hi:[0,1,1]
	v_pk_fma_f32 v[42:43], v[198:199], v[10:11], v[42:43] op_sel_hi:[0,1,1]
	v_pk_fma_f32 v[44:45], v[198:199], v[12:13], v[44:45] op_sel_hi:[0,1,1]
	v_pk_fma_f32 v[46:47], v[198:199], v[14:15], v[46:47] op_sel_hi:[0,1,1]
	v_pk_fma_f32 v[48:49], v[198:199], v[16:17], v[48:49] op_sel_hi:[0,1,1]
	v_pk_fma_f32 v[50:51], v[198:199], v[18:19], v[50:51] op_sel_hi:[0,1,1]
	v_pk_fma_f32 v[52:53], v[198:199], v[20:21], v[52:53] op_sel_hi:[0,1,1]
	v_pk_fma_f32 v[54:55], v[198:199], v[22:23], v[54:55] op_sel_hi:[0,1,1]
	v_pk_fma_f32 v[56:57], v[198:199], v[24:25], v[56:57] op_sel_hi:[0,1,1]
	v_pk_fma_f32 v[58:59], v[198:199], v[26:27], v[58:59] op_sel_hi:[0,1,1]
	v_pk_fma_f32 v[60:61], v[198:199], v[28:29], v[60:61] op_sel_hi:[0,1,1]
	v_pk_fma_f32 v[62:63], v[198:199], v[30:31], v[62:63] op_sel_hi:[0,1,1]
	s_waitcnt vmcnt(17)
	v_cvt_scalef32_pk32_f32_fp6 v[0:31], v[138:143], 1.0
	v_pk_fma_f32 v[32:33], v[198:199], v[0:1], v[32:33] op_sel:[1,0,0] op_sel_hi:[1,1,1]
	v_pk_fma_f32 v[34:35], v[198:199], v[2:3], v[34:35] op_sel:[1,0,0] op_sel_hi:[1,1,1]
	v_pk_fma_f32 v[36:37], v[198:199], v[4:5], v[36:37] op_sel:[1,0,0] op_sel_hi:[1,1,1]
	v_pk_fma_f32 v[38:39], v[198:199], v[6:7], v[38:39] op_sel:[1,0,0] op_sel_hi:[1,1,1]
	v_pk_fma_f32 v[40:41], v[198:199], v[8:9], v[40:41] op_sel:[1,0,0] op_sel_hi:[1,1,1]
	v_pk_fma_f32 v[42:43], v[198:199], v[10:11], v[42:43] op_sel:[1,0,0] op_sel_hi:[1,1,1]
	v_pk_fma_f32 v[44:45], v[198:199], v[12:13], v[44:45] op_sel:[1,0,0] op_sel_hi:[1,1,1]
	v_pk_fma_f32 v[46:47], v[198:199], v[14:15], v[46:47] op_sel:[1,0,0] op_sel_hi:[1,1,1]
	v_pk_fma_f32 v[48:49], v[198:199], v[16:17], v[48:49] op_sel:[1,0,0] op_sel_hi:[1,1,1]
	v_pk_fma_f32 v[50:51], v[198:199], v[18:19], v[50:51] op_sel:[1,0,0] op_sel_hi:[1,1,1]
	v_pk_fma_f32 v[52:53], v[198:199], v[20:21], v[52:53] op_sel:[1,0,0] op_sel_hi:[1,1,1]
	v_pk_fma_f32 v[54:55], v[198:199], v[22:23], v[54:55] op_sel:[1,0,0] op_sel_hi:[1,1,1]
	v_pk_fma_f32 v[56:57], v[198:199], v[24:25], v[56:57] op_sel:[1,0,0] op_sel_hi:[1,1,1]
	v_pk_fma_f32 v[58:59], v[198:199], v[26:27], v[58:59] op_sel:[1,0,0] op_sel_hi:[1,1,1]
	v_pk_fma_f32 v[60:61], v[198:199], v[28:29], v[60:61] op_sel:[1,0,0] op_sel_hi:[1,1,1]
	v_pk_fma_f32 v[62:63], v[198:199], v[30:31], v[62:63] op_sel:[1,0,0] op_sel_hi:[1,1,1]
	s_waitcnt lgkmcnt(0)
	global_load_dwordx2 v[64:65], v225, s[32:33]
	global_load_dwordx4 v[66:69], v226, s[58:59]
	v_mad_u32_u24 v217, v80, s52, v220
	v_add_u32_e32 v218, v217, v221
	global_load_dwordx4 v[96:99], v217, s[30:31]
	global_load_dwordx2 v[100:101], v218, s[30:31]
	v_mad_u32_u24 v217, v81, s52, v220
	v_add_u32_e32 v218, v217, v221
	global_load_dwordx4 v[102:105], v217, s[30:31]
	global_load_dwordx2 v[106:107], v218, s[30:31]
	v_mad_u32_u24 v217, v82, s52, v220
	v_add_u32_e32 v218, v217, v221
	global_load_dwordx4 v[108:111], v217, s[30:31]
	global_load_dwordx2 v[112:113], v218, s[30:31]
	v_mad_u32_u24 v217, v83, s52, v220
	v_add_u32_e32 v218, v217, v221
	global_load_dwordx4 v[114:117], v217, s[30:31]
	global_load_dwordx2 v[118:119], v218, s[30:31]
	v_mad_u32_u24 v217, v84, s52, v220
	v_add_u32_e32 v218, v217, v221
	global_load_dwordx4 v[120:123], v217, s[30:31]
	global_load_dwordx2 v[124:125], v218, s[30:31]
	v_mad_u32_u24 v217, v85, s52, v220
	v_add_u32_e32 v218, v217, v221
	global_load_dwordx4 v[126:129], v217, s[30:31]
	global_load_dwordx2 v[130:131], v218, s[30:31]
	v_mad_u32_u24 v217, v86, s52, v220
	v_add_u32_e32 v218, v217, v221
	global_load_dwordx4 v[132:135], v217, s[30:31]
	global_load_dwordx2 v[136:137], v218, s[30:31]
	v_mad_u32_u24 v217, v87, s52, v220
	v_add_u32_e32 v218, v217, v221
	global_load_dwordx4 v[138:141], v217, s[30:31]
	global_load_dwordx2 v[142:143], v218, s[30:31]
	s_waitcnt vmcnt(33)
	v_cvt_scalef32_pk32_f32_fp6 v[0:31], v[144:149], 1.0
	v_pk_fma_f32 v[32:33], v[200:201], v[0:1], v[32:33] op_sel_hi:[0,1,1]
	v_pk_fma_f32 v[34:35], v[200:201], v[2:3], v[34:35] op_sel_hi:[0,1,1]
	v_pk_fma_f32 v[36:37], v[200:201], v[4:5], v[36:37] op_sel_hi:[0,1,1]
	v_pk_fma_f32 v[38:39], v[200:201], v[6:7], v[38:39] op_sel_hi:[0,1,1]
	v_pk_fma_f32 v[40:41], v[200:201], v[8:9], v[40:41] op_sel_hi:[0,1,1]
	v_pk_fma_f32 v[42:43], v[200:201], v[10:11], v[42:43] op_sel_hi:[0,1,1]
	v_pk_fma_f32 v[44:45], v[200:201], v[12:13], v[44:45] op_sel_hi:[0,1,1]
	v_pk_fma_f32 v[46:47], v[200:201], v[14:15], v[46:47] op_sel_hi:[0,1,1]
	v_pk_fma_f32 v[48:49], v[200:201], v[16:17], v[48:49] op_sel_hi:[0,1,1]
	v_pk_fma_f32 v[50:51], v[200:201], v[18:19], v[50:51] op_sel_hi:[0,1,1]
	v_pk_fma_f32 v[52:53], v[200:201], v[20:21], v[52:53] op_sel_hi:[0,1,1]
	v_pk_fma_f32 v[54:55], v[200:201], v[22:23], v[54:55] op_sel_hi:[0,1,1]
	v_pk_fma_f32 v[56:57], v[200:201], v[24:25], v[56:57] op_sel_hi:[0,1,1]
	v_pk_fma_f32 v[58:59], v[200:201], v[26:27], v[58:59] op_sel_hi:[0,1,1]
	v_pk_fma_f32 v[60:61], v[200:201], v[28:29], v[60:61] op_sel_hi:[0,1,1]
	v_pk_fma_f32 v[62:63], v[200:201], v[30:31], v[62:63] op_sel_hi:[0,1,1]
	s_waitcnt vmcnt(31)
	v_cvt_scalef32_pk32_f32_fp6 v[0:31], v[150:155], 1.0
	v_pk_fma_f32 v[32:33], v[200:201], v[0:1], v[32:33] op_sel:[1,0,0] op_sel_hi:[1,1,1]
	v_pk_fma_f32 v[34:35], v[200:201], v[2:3], v[34:35] op_sel:[1,0,0] op_sel_hi:[1,1,1]
	v_pk_fma_f32 v[36:37], v[200:201], v[4:5], v[36:37] op_sel:[1,0,0] op_sel_hi:[1,1,1]
	v_pk_fma_f32 v[38:39], v[200:201], v[6:7], v[38:39] op_sel:[1,0,0] op_sel_hi:[1,1,1]
	v_pk_fma_f32 v[40:41], v[200:201], v[8:9], v[40:41] op_sel:[1,0,0] op_sel_hi:[1,1,1]
	v_pk_fma_f32 v[42:43], v[200:201], v[10:11], v[42:43] op_sel:[1,0,0] op_sel_hi:[1,1,1]
	v_pk_fma_f32 v[44:45], v[200:201], v[12:13], v[44:45] op_sel:[1,0,0] op_sel_hi:[1,1,1]
	v_pk_fma_f32 v[46:47], v[200:201], v[14:15], v[46:47] op_sel:[1,0,0] op_sel_hi:[1,1,1]
	v_pk_fma_f32 v[48:49], v[200:201], v[16:17], v[48:49] op_sel:[1,0,0] op_sel_hi:[1,1,1]
	v_pk_fma_f32 v[50:51], v[200:201], v[18:19], v[50:51] op_sel:[1,0,0] op_sel_hi:[1,1,1]
	v_pk_fma_f32 v[52:53], v[200:201], v[20:21], v[52:53] op_sel:[1,0,0] op_sel_hi:[1,1,1]
	v_pk_fma_f32 v[54:55], v[200:201], v[22:23], v[54:55] op_sel:[1,0,0] op_sel_hi:[1,1,1]
	v_pk_fma_f32 v[56:57], v[200:201], v[24:25], v[56:57] op_sel:[1,0,0] op_sel_hi:[1,1,1]
	v_pk_fma_f32 v[58:59], v[200:201], v[26:27], v[58:59] op_sel:[1,0,0] op_sel_hi:[1,1,1]
	v_pk_fma_f32 v[60:61], v[200:201], v[28:29], v[60:61] op_sel:[1,0,0] op_sel_hi:[1,1,1]
	v_pk_fma_f32 v[62:63], v[200:201], v[30:31], v[62:63] op_sel:[1,0,0] op_sel_hi:[1,1,1]
	s_waitcnt vmcnt(29)
	v_cvt_scalef32_pk32_f32_fp6 v[0:31], v[156:161], 1.0
	v_pk_fma_f32 v[32:33], v[202:203], v[0:1], v[32:33] op_sel_hi:[0,1,1]
	v_pk_fma_f32 v[34:35], v[202:203], v[2:3], v[34:35] op_sel_hi:[0,1,1]
	v_pk_fma_f32 v[36:37], v[202:203], v[4:5], v[36:37] op_sel_hi:[0,1,1]
	v_pk_fma_f32 v[38:39], v[202:203], v[6:7], v[38:39] op_sel_hi:[0,1,1]
	v_pk_fma_f32 v[40:41], v[202:203], v[8:9], v[40:41] op_sel_hi:[0,1,1]
	v_pk_fma_f32 v[42:43], v[202:203], v[10:11], v[42:43] op_sel_hi:[0,1,1]
	v_pk_fma_f32 v[44:45], v[202:203], v[12:13], v[44:45] op_sel_hi:[0,1,1]
	v_pk_fma_f32 v[46:47], v[202:203], v[14:15], v[46:47] op_sel_hi:[0,1,1]
	v_pk_fma_f32 v[48:49], v[202:203], v[16:17], v[48:49] op_sel_hi:[0,1,1]
	v_pk_fma_f32 v[50:51], v[202:203], v[18:19], v[50:51] op_sel_hi:[0,1,1]
	v_pk_fma_f32 v[52:53], v[202:203], v[20:21], v[52:53] op_sel_hi:[0,1,1]
	v_pk_fma_f32 v[54:55], v[202:203], v[22:23], v[54:55] op_sel_hi:[0,1,1]
	v_pk_fma_f32 v[56:57], v[202:203], v[24:25], v[56:57] op_sel_hi:[0,1,1]
	v_pk_fma_f32 v[58:59], v[202:203], v[26:27], v[58:59] op_sel_hi:[0,1,1]
	v_pk_fma_f32 v[60:61], v[202:203], v[28:29], v[60:61] op_sel_hi:[0,1,1]
	v_pk_fma_f32 v[62:63], v[202:203], v[30:31], v[62:63] op_sel_hi:[0,1,1]
	s_waitcnt vmcnt(27)
	v_cvt_scalef32_pk32_f32_fp6 v[0:31], v[162:167], 1.0
	v_pk_fma_f32 v[32:33], v[202:203], v[0:1], v[32:33] op_sel:[1,0,0] op_sel_hi:[1,1,1]
	v_pk_fma_f32 v[34:35], v[202:203], v[2:3], v[34:35] op_sel:[1,0,0] op_sel_hi:[1,1,1]
	v_pk_fma_f32 v[36:37], v[202:203], v[4:5], v[36:37] op_sel:[1,0,0] op_sel_hi:[1,1,1]
	v_pk_fma_f32 v[38:39], v[202:203], v[6:7], v[38:39] op_sel:[1,0,0] op_sel_hi:[1,1,1]
	v_pk_fma_f32 v[40:41], v[202:203], v[8:9], v[40:41] op_sel:[1,0,0] op_sel_hi:[1,1,1]
	v_pk_fma_f32 v[42:43], v[202:203], v[10:11], v[42:43] op_sel:[1,0,0] op_sel_hi:[1,1,1]
	v_pk_fma_f32 v[44:45], v[202:203], v[12:13], v[44:45] op_sel:[1,0,0] op_sel_hi:[1,1,1]
	v_pk_fma_f32 v[46:47], v[202:203], v[14:15], v[46:47] op_sel:[1,0,0] op_sel_hi:[1,1,1]
	v_pk_fma_f32 v[48:49], v[202:203], v[16:17], v[48:49] op_sel:[1,0,0] op_sel_hi:[1,1,1]
	v_pk_fma_f32 v[50:51], v[202:203], v[18:19], v[50:51] op_sel:[1,0,0] op_sel_hi:[1,1,1]
	v_pk_fma_f32 v[52:53], v[202:203], v[20:21], v[52:53] op_sel:[1,0,0] op_sel_hi:[1,1,1]
	v_pk_fma_f32 v[54:55], v[202:203], v[22:23], v[54:55] op_sel:[1,0,0] op_sel_hi:[1,1,1]
	v_pk_fma_f32 v[56:57], v[202:203], v[24:25], v[56:57] op_sel:[1,0,0] op_sel_hi:[1,1,1]
	v_pk_fma_f32 v[58:59], v[202:203], v[26:27], v[58:59] op_sel:[1,0,0] op_sel_hi:[1,1,1]
	v_pk_fma_f32 v[60:61], v[202:203], v[28:29], v[60:61] op_sel:[1,0,0] op_sel_hi:[1,1,1]
	v_pk_fma_f32 v[62:63], v[202:203], v[30:31], v[62:63] op_sel:[1,0,0] op_sel_hi:[1,1,1]
	s_waitcnt vmcnt(25)
	v_cvt_scalef32_pk32_f32_fp6 v[0:31], v[168:173], 1.0
	v_pk_fma_f32 v[32:33], v[204:205], v[0:1], v[32:33] op_sel_hi:[0,1,1]
	v_pk_fma_f32 v[34:35], v[204:205], v[2:3], v[34:35] op_sel_hi:[0,1,1]
	v_pk_fma_f32 v[36:37], v[204:205], v[4:5], v[36:37] op_sel_hi:[0,1,1]
	v_pk_fma_f32 v[38:39], v[204:205], v[6:7], v[38:39] op_sel_hi:[0,1,1]
	v_pk_fma_f32 v[40:41], v[204:205], v[8:9], v[40:41] op_sel_hi:[0,1,1]
	v_pk_fma_f32 v[42:43], v[204:205], v[10:11], v[42:43] op_sel_hi:[0,1,1]
	v_pk_fma_f32 v[44:45], v[204:205], v[12:13], v[44:45] op_sel_hi:[0,1,1]
	v_pk_fma_f32 v[46:47], v[204:205], v[14:15], v[46:47] op_sel_hi:[0,1,1]
	v_pk_fma_f32 v[48:49], v[204:205], v[16:17], v[48:49] op_sel_hi:[0,1,1]
	v_pk_fma_f32 v[50:51], v[204:205], v[18:19], v[50:51] op_sel_hi:[0,1,1]
	v_pk_fma_f32 v[52:53], v[204:205], v[20:21], v[52:53] op_sel_hi:[0,1,1]
	v_pk_fma_f32 v[54:55], v[204:205], v[22:23], v[54:55] op_sel_hi:[0,1,1]
	v_pk_fma_f32 v[56:57], v[204:205], v[24:25], v[56:57] op_sel_hi:[0,1,1]
	v_pk_fma_f32 v[58:59], v[204:205], v[26:27], v[58:59] op_sel_hi:[0,1,1]
	v_pk_fma_f32 v[60:61], v[204:205], v[28:29], v[60:61] op_sel_hi:[0,1,1]
	v_pk_fma_f32 v[62:63], v[204:205], v[30:31], v[62:63] op_sel_hi:[0,1,1]
	s_waitcnt vmcnt(23)
	v_cvt_scalef32_pk32_f32_fp6 v[0:31], v[174:179], 1.0
	v_pk_fma_f32 v[32:33], v[204:205], v[0:1], v[32:33] op_sel:[1,0,0] op_sel_hi:[1,1,1]
	v_pk_fma_f32 v[34:35], v[204:205], v[2:3], v[34:35] op_sel:[1,0,0] op_sel_hi:[1,1,1]
	v_pk_fma_f32 v[36:37], v[204:205], v[4:5], v[36:37] op_sel:[1,0,0] op_sel_hi:[1,1,1]
	v_pk_fma_f32 v[38:39], v[204:205], v[6:7], v[38:39] op_sel:[1,0,0] op_sel_hi:[1,1,1]
	v_pk_fma_f32 v[40:41], v[204:205], v[8:9], v[40:41] op_sel:[1,0,0] op_sel_hi:[1,1,1]
	v_pk_fma_f32 v[42:43], v[204:205], v[10:11], v[42:43] op_sel:[1,0,0] op_sel_hi:[1,1,1]
	v_pk_fma_f32 v[44:45], v[204:205], v[12:13], v[44:45] op_sel:[1,0,0] op_sel_hi:[1,1,1]
	v_pk_fma_f32 v[46:47], v[204:205], v[14:15], v[46:47] op_sel:[1,0,0] op_sel_hi:[1,1,1]
	v_pk_fma_f32 v[48:49], v[204:205], v[16:17], v[48:49] op_sel:[1,0,0] op_sel_hi:[1,1,1]
	v_pk_fma_f32 v[50:51], v[204:205], v[18:19], v[50:51] op_sel:[1,0,0] op_sel_hi:[1,1,1]
	v_pk_fma_f32 v[52:53], v[204:205], v[20:21], v[52:53] op_sel:[1,0,0] op_sel_hi:[1,1,1]
	v_pk_fma_f32 v[54:55], v[204:205], v[22:23], v[54:55] op_sel:[1,0,0] op_sel_hi:[1,1,1]
	v_pk_fma_f32 v[56:57], v[204:205], v[24:25], v[56:57] op_sel:[1,0,0] op_sel_hi:[1,1,1]
	v_pk_fma_f32 v[58:59], v[204:205], v[26:27], v[58:59] op_sel:[1,0,0] op_sel_hi:[1,1,1]
	v_pk_fma_f32 v[60:61], v[204:205], v[28:29], v[60:61] op_sel:[1,0,0] op_sel_hi:[1,1,1]
	v_pk_fma_f32 v[62:63], v[204:205], v[30:31], v[62:63] op_sel:[1,0,0] op_sel_hi:[1,1,1]
	s_waitcnt vmcnt(21)
	v_cvt_scalef32_pk32_f32_fp6 v[0:31], v[180:185], 1.0
	v_pk_fma_f32 v[32:33], v[206:207], v[0:1], v[32:33] op_sel_hi:[0,1,1]
	v_pk_fma_f32 v[34:35], v[206:207], v[2:3], v[34:35] op_sel_hi:[0,1,1]
	v_pk_fma_f32 v[36:37], v[206:207], v[4:5], v[36:37] op_sel_hi:[0,1,1]
	v_pk_fma_f32 v[38:39], v[206:207], v[6:7], v[38:39] op_sel_hi:[0,1,1]
	v_pk_fma_f32 v[40:41], v[206:207], v[8:9], v[40:41] op_sel_hi:[0,1,1]
	v_pk_fma_f32 v[42:43], v[206:207], v[10:11], v[42:43] op_sel_hi:[0,1,1]
	v_pk_fma_f32 v[44:45], v[206:207], v[12:13], v[44:45] op_sel_hi:[0,1,1]
	v_pk_fma_f32 v[46:47], v[206:207], v[14:15], v[46:47] op_sel_hi:[0,1,1]
	v_pk_fma_f32 v[48:49], v[206:207], v[16:17], v[48:49] op_sel_hi:[0,1,1]
	v_pk_fma_f32 v[50:51], v[206:207], v[18:19], v[50:51] op_sel_hi:[0,1,1]
	v_pk_fma_f32 v[52:53], v[206:207], v[20:21], v[52:53] op_sel_hi:[0,1,1]
	v_pk_fma_f32 v[54:55], v[206:207], v[22:23], v[54:55] op_sel_hi:[0,1,1]
	v_pk_fma_f32 v[56:57], v[206:207], v[24:25], v[56:57] op_sel_hi:[0,1,1]
	v_pk_fma_f32 v[58:59], v[206:207], v[26:27], v[58:59] op_sel_hi:[0,1,1]
	v_pk_fma_f32 v[60:61], v[206:207], v[28:29], v[60:61] op_sel_hi:[0,1,1]
	v_pk_fma_f32 v[62:63], v[206:207], v[30:31], v[62:63] op_sel_hi:[0,1,1]
	s_waitcnt vmcnt(19)
	v_cvt_scalef32_pk32_f32_fp6 v[0:31], v[186:191], 1.0
	v_pk_fma_f32 v[32:33], v[206:207], v[0:1], v[32:33] op_sel:[1,0,0] op_sel_hi:[1,1,1]
	v_pk_fma_f32 v[34:35], v[206:207], v[2:3], v[34:35] op_sel:[1,0,0] op_sel_hi:[1,1,1]
	v_pk_fma_f32 v[36:37], v[206:207], v[4:5], v[36:37] op_sel:[1,0,0] op_sel_hi:[1,1,1]
	v_pk_fma_f32 v[38:39], v[206:207], v[6:7], v[38:39] op_sel:[1,0,0] op_sel_hi:[1,1,1]
	v_pk_fma_f32 v[40:41], v[206:207], v[8:9], v[40:41] op_sel:[1,0,0] op_sel_hi:[1,1,1]
	v_pk_fma_f32 v[42:43], v[206:207], v[10:11], v[42:43] op_sel:[1,0,0] op_sel_hi:[1,1,1]
	v_pk_fma_f32 v[44:45], v[206:207], v[12:13], v[44:45] op_sel:[1,0,0] op_sel_hi:[1,1,1]
	v_pk_fma_f32 v[46:47], v[206:207], v[14:15], v[46:47] op_sel:[1,0,0] op_sel_hi:[1,1,1]
	v_pk_fma_f32 v[48:49], v[206:207], v[16:17], v[48:49] op_sel:[1,0,0] op_sel_hi:[1,1,1]
	v_pk_fma_f32 v[50:51], v[206:207], v[18:19], v[50:51] op_sel:[1,0,0] op_sel_hi:[1,1,1]
	v_pk_fma_f32 v[52:53], v[206:207], v[20:21], v[52:53] op_sel:[1,0,0] op_sel_hi:[1,1,1]
	v_pk_fma_f32 v[54:55], v[206:207], v[22:23], v[54:55] op_sel:[1,0,0] op_sel_hi:[1,1,1]
	v_pk_fma_f32 v[56:57], v[206:207], v[24:25], v[56:57] op_sel:[1,0,0] op_sel_hi:[1,1,1]
	v_pk_fma_f32 v[58:59], v[206:207], v[26:27], v[58:59] op_sel:[1,0,0] op_sel_hi:[1,1,1]
	v_pk_fma_f32 v[60:61], v[206:207], v[28:29], v[60:61] op_sel:[1,0,0] op_sel_hi:[1,1,1]
	v_pk_fma_f32 v[62:63], v[206:207], v[30:31], v[62:63] op_sel:[1,0,0] op_sel_hi:[1,1,1]
	v_mad_u32_u24 v217, v88, s52, v220
	v_add_u32_e32 v218, v217, v221
	global_load_dwordx4 v[144:147], v217, s[30:31]
	global_load_dwordx2 v[148:149], v218, s[30:31]
	v_mad_u32_u24 v217, v89, s52, v220
	v_add_u32_e32 v218, v217, v221
	global_load_dwordx4 v[150:153], v217, s[30:31]
	global_load_dwordx2 v[154:155], v218, s[30:31]
	v_mad_u32_u24 v217, v90, s52, v220
	v_add_u32_e32 v218, v217, v221
	global_load_dwordx4 v[156:159], v217, s[30:31]
	global_load_dwordx2 v[160:161], v218, s[30:31]
	v_mad_u32_u24 v217, v91, s52, v220
	v_add_u32_e32 v218, v217, v221
	global_load_dwordx4 v[162:165], v217, s[30:31]
	global_load_dwordx2 v[166:167], v218, s[30:31]
	v_mad_u32_u24 v217, v92, s52, v220
	v_add_u32_e32 v218, v217, v221
	global_load_dwordx4 v[168:171], v217, s[30:31]
	global_load_dwordx2 v[172:173], v218, s[30:31]
	v_mad_u32_u24 v217, v93, s52, v220
	v_add_u32_e32 v218, v217, v221
	global_load_dwordx4 v[174:177], v217, s[30:31]
	global_load_dwordx2 v[178:179], v218, s[30:31]
	v_mad_u32_u24 v217, v94, s52, v220
	v_add_u32_e32 v218, v217, v221
	global_load_dwordx4 v[180:183], v217, s[30:31]
	global_load_dwordx2 v[184:185], v218, s[30:31]
	v_mad_u32_u24 v217, v95, s52, v220
	v_add_u32_e32 v218, v217, v221
	global_load_dwordx4 v[186:189], v217, s[30:31]
	global_load_dwordx2 v[190:191], v218, s[30:31]
	v_cndmask_b32_e64 v212, v48, v32, s[46:47]
	v_cndmask_b32_e64 v213, v32, v48, s[46:47]
	v_cndmask_b32_e64 v214, v49, v33, s[46:47]
	v_cndmask_b32_e64 v215, v33, v49, s[46:47]
	v_add_f32_dpp v32, v212, v213 row_ror:8 row_mask:0xf bank_mask:0xf
	v_add_f32_dpp v33, v214, v215 row_ror:8 row_mask:0xf bank_mask:0xf
	v_cndmask_b32_e64 v212, v50, v34, s[46:47]
	v_cndmask_b32_e64 v213, v34, v50, s[46:47]
	v_cndmask_b32_e64 v214, v51, v35, s[46:47]
	v_cndmask_b32_e64 v215, v35, v51, s[46:47]
	v_add_f32_dpp v34, v212, v213 row_ror:8 row_mask:0xf bank_mask:0xf
	v_add_f32_dpp v35, v214, v215 row_ror:8 row_mask:0xf bank_mask:0xf
	v_cndmask_b32_e64 v212, v52, v36, s[46:47]
	v_cndmask_b32_e64 v213, v36, v52, s[46:47]
	v_cndmask_b32_e64 v214, v53, v37, s[46:47]
	v_cndmask_b32_e64 v215, v37, v53, s[46:47]
	v_add_f32_dpp v36, v212, v213 row_ror:8 row_mask:0xf bank_mask:0xf
	v_add_f32_dpp v37, v214, v215 row_ror:8 row_mask:0xf bank_mask:0xf
	v_cndmask_b32_e64 v212, v54, v38, s[46:47]
	v_cndmask_b32_e64 v213, v38, v54, s[46:47]
	v_cndmask_b32_e64 v214, v55, v39, s[46:47]
	v_cndmask_b32_e64 v215, v39, v55, s[46:47]
	v_add_f32_dpp v38, v212, v213 row_ror:8 row_mask:0xf bank_mask:0xf
	v_add_f32_dpp v39, v214, v215 row_ror:8 row_mask:0xf bank_mask:0xf
	v_cndmask_b32_e64 v212, v56, v40, s[46:47]
	v_cndmask_b32_e64 v213, v40, v56, s[46:47]
	v_cndmask_b32_e64 v214, v57, v41, s[46:47]
	v_cndmask_b32_e64 v215, v41, v57, s[46:47]
	v_add_f32_dpp v40, v212, v213 row_ror:8 row_mask:0xf bank_mask:0xf
	v_add_f32_dpp v41, v214, v215 row_ror:8 row_mask:0xf bank_mask:0xf
	v_cndmask_b32_e64 v212, v58, v42, s[46:47]
	v_cndmask_b32_e64 v213, v42, v58, s[46:47]
	v_cndmask_b32_e64 v214, v59, v43, s[46:47]
	v_cndmask_b32_e64 v215, v43, v59, s[46:47]
	v_add_f32_dpp v42, v212, v213 row_ror:8 row_mask:0xf bank_mask:0xf
	v_add_f32_dpp v43, v214, v215 row_ror:8 row_mask:0xf bank_mask:0xf
	v_cndmask_b32_e64 v212, v60, v44, s[46:47]
	v_cndmask_b32_e64 v213, v44, v60, s[46:47]
	v_cndmask_b32_e64 v214, v61, v45, s[46:47]
	v_cndmask_b32_e64 v215, v45, v61, s[46:47]
	v_add_f32_dpp v44, v212, v213 row_ror:8 row_mask:0xf bank_mask:0xf
	v_add_f32_dpp v45, v214, v215 row_ror:8 row_mask:0xf bank_mask:0xf
	v_cndmask_b32_e64 v212, v62, v46, s[46:47]
	v_cndmask_b32_e64 v213, v46, v62, s[46:47]
	v_cndmask_b32_e64 v214, v63, v47, s[46:47]
	v_cndmask_b32_e64 v215, v47, v63, s[46:47]
	v_add_f32_dpp v46, v212, v213 row_ror:8 row_mask:0xf bank_mask:0xf
	v_add_f32_dpp v47, v214, v215 row_ror:8 row_mask:0xf bank_mask:0xf
	v_cndmask_b32_e64 v0, v40, v32, s[48:49]
	v_cndmask_b32_e64 v32, v32, v40, s[48:49]
	v_cndmask_b32_e64 v1, v41, v33, s[48:49]
	v_cndmask_b32_e64 v33, v33, v41, s[48:49]
	v_cndmask_b32_e64 v2, v42, v34, s[48:49]
	v_cndmask_b32_e64 v34, v34, v42, s[48:49]
	v_cndmask_b32_e64 v3, v43, v35, s[48:49]
	v_cndmask_b32_e64 v35, v35, v43, s[48:49]
	v_cndmask_b32_e64 v4, v44, v36, s[48:49]
	v_cndmask_b32_e64 v36, v36, v44, s[48:49]
	v_cndmask_b32_e64 v5, v45, v37, s[48:49]
	v_cndmask_b32_e64 v37, v37, v45, s[48:49]
	v_cndmask_b32_e64 v6, v46, v38, s[48:49]
	v_cndmask_b32_e64 v38, v38, v46, s[48:49]
	v_cndmask_b32_e64 v7, v47, v39, s[48:49]
	v_cndmask_b32_e64 v39, v39, v47, s[48:49]
	ds_swizzle_b32 v0, v0 offset:0x401f
	ds_swizzle_b32 v1, v1 offset:0x401f
	ds_swizzle_b32 v2, v2 offset:0x401f
	ds_swizzle_b32 v3, v3 offset:0x401f
	ds_swizzle_b32 v4, v4 offset:0x401f
	ds_swizzle_b32 v5, v5 offset:0x401f
	ds_swizzle_b32 v6, v6 offset:0x401f
	ds_swizzle_b32 v7, v7 offset:0x401f
	s_waitcnt lgkmcnt(0)
	v_add_f32_e32 v32, v32, v0
	v_add_f32_e32 v33, v33, v1
	v_add_f32_e32 v34, v34, v2
	v_add_f32_e32 v35, v35, v3
	v_add_f32_e32 v36, v36, v4
	v_add_f32_e32 v37, v37, v5
	v_add_f32_e32 v38, v38, v6
	v_add_f32_e32 v39, v39, v7
	v_cndmask_b32_e64 v0, v36, v32, s[50:51]
	v_cndmask_b32_e64 v32, v32, v36, s[50:51]
	v_cndmask_b32_e64 v1, v37, v33, s[50:51]
	v_cndmask_b32_e64 v33, v33, v37, s[50:51]
	v_cndmask_b32_e64 v2, v38, v34, s[50:51]
	v_cndmask_b32_e64 v34, v34, v38, s[50:51]
	v_cndmask_b32_e64 v3, v39, v35, s[50:51]
	v_cndmask_b32_e64 v35, v35, v39, s[50:51]
	ds_bpermute_b32 v0, v227, v0
	ds_bpermute_b32 v1, v227, v1
	ds_bpermute_b32 v2, v227, v2
	ds_bpermute_b32 v3, v227, v3
	s_waitcnt lgkmcnt(0)
	v_add_f32_e32 v32, v32, v0
	v_add_f32_e32 v33, v33, v1
	v_add_f32_e32 v34, v34, v2
	v_add_f32_e32 v35, v35, v3
	v_lshlrev_b32_e32 v8, 16, v72
	v_and_b32_e32 v9, 0xffff0000, v72
	v_lshlrev_b32_e32 v10, 16, v73
	v_and_b32_e32 v11, 0xffff0000, v73
	v_pk_fma_f32 v[8:9], v[74:75], v[32:33], v[8:9]
	v_pk_fma_f32 v[10:11], v[76:77], v[34:35], v[10:11]
	s_cmp_eq_u32 s80, 0
	s_cbranch_scc1 .Lex_vskip
	global_store_dwordx4 v226, v[8:11], s[78:79]
	s_branch .Lex_vdone
.Lex_vskip:
	global_load_dword v219, v231, s[28:29]
.Lex_vdone:
	s_mov_b32 s7, s53
	s_mov_b32 s8, s54
	s_cmp_lt_u32 s8, 16
	s_cbranch_scc1 .Lex_vloop
	s_waitcnt vmcnt(0) lgkmcnt(0)
	s_lshl_b32 s34, s5, 3
	s_add_i32 s6, s6, s34
	s_cmp_lt_u32 s6, 0x4000
	s_cbranch_scc1 .Lex_chunk
